# diff-attention stage loop hand-rescheduled: P.V of stage t-1 interleaved with softmax VALU of stage t (P kept one stage in registers), permlane32_swap instead of ds_bpermute; on top of SB prefetch-ove
# speedup vs baseline: 1.0195x; 1.0116x over previous
; #define DF_WAITBAR(N) asm volatile("s_waitcnt vmcnt(" #N ") lgkmcnt(0)\n\ts_barrier" ::: "memory")
; DI void diff_unit(const Args& A, const bf16_t* QKV, bf16_t* ATT, unsigned char* lds, LAS unsigned char* lds3, int b, int head, int qb, int tid, int wid, int lane) {
;     const int r32 = lane & 31, hi = lane >> 5, comp = wid >> 2, wq = wid & 3;
;     const size_t rowbase = (size_t)b * SEQ;
;     const int q0 = qb * 128 + wq * 32;
;     const int qcol = 1536 + head * 128 + comp * 64;
;     bf16x8 qf[4];
; #pragma unroll
;     for (int c = 0; c < 4; ++c) qf[c] = *(const bf16x8*)(QKV + (rowbase + q0 + r32) * QKVW + qcol + 16 * c + 8 * hi);
;     f32x16 o[4];
; #pragma unroll
;     for (int t = 0; t < 4; ++t)
; #pragma unroll
;         for (int i = 0; i < 16; ++i) o[t][i] = 0.f;
;     float m = -INFINITY, l = 0.f;
;     const int nst = 2 * (qb + 1);
;     const unsigned ldsb = (unsigned)(uintptr_t)lds3;
;     const int kkey = 8 * wid + (lane >> 3), kch = (lane & 7) ^ ((kkey >> 1) & 7);
;     const int vi0 = 2 * wid, vi1 = 2 * wid + 1;
;     const bf16_t* sbase = QKV + rowbase * QKVW + head * 128;
;     const unsigned oK = (unsigned)((kkey * QKVW + 2048 + kch * 8) * 2);
;     const unsigned oV0 = (unsigned)(((16 * (vi0 & 3) + (lane >> 2)) * QKVW + 2560 + ((vi0 >> 2) * 4 + (lane & 3)) * 8) * 2);
;     const unsigned oV1 = (unsigned)(((16 * (vi1 & 3) + (lane >> 2)) * QKVW + 2560 + ((vi1 >> 2) * 4 + (lane & 3)) * 8) * 2);
;     const unsigned dK = (unsigned)__builtin_amdgcn_readfirstlane(wid * 1024);
;     const unsigned dV0 = (unsigned)__builtin_amdgcn_readfirstlane(DF_V + (vi0 >> 2) * 4096 + (vi0 & 3) * 1024), dV1 = (unsigned)__builtin_amdgcn_readfirstlane(DF_V + (vi1 >> 2) * 4096 + (vi1 & 3) * 1024);
;     ...
;     DF_DMA(0, 0); DF_DMA(1, 1);
;     asm volatile("" : "+v"(qf[0]), "+v"(qf[1]), "+v"(qf[2]), "+v"(qf[3]));
;     DF_WAITBAR(4);
;     const int vlane = (4 * hi + ((lane & 15) >> 2)) * 64 + ((lane >> 4) & 1) * 32 + (lane & 3) * 8;
;     const bool skew = false;
;     bf16x8 pp[4]; { const bf16x8 z8 = {0, 0, 0, 0, 0, 0, 0, 0}; pp[0] = z8; pp[1] = z8; pp[2] = z8; pp[3] = z8; } int pvo = vlane; bool have_prev = false;
;     for (int t = 0; t < nst; ++t) {
;         { const int tl = (t + 2 < nst) ? t + 2 : nst - 1; DF_DMA(tl, (t + 2) & 3); }
.LBB0_278:
	s_and_b32 s49, s7, 63
	s_ashr_i32 s6, s7, 8
	s_xor_b32 s24, s49, 0x7f
	s_bfe_u32 s22, s7, 0x20006
	s_ashr_i32 s7, s6, 31
	s_lshl_b32 s25, s24, 7
	s_lshl_b64 s[26:27], s[6:7], 14
	s_or_b32 s7, s25, s34
	v_or_b32_e32 v1, s7, v129
	s_lshl_b32 s48, s22, 7
	v_or_b32_e32 v154, s26, v1
	v_mad_u64_u32 v[2:3], s[8:9], v154, s43, v[140:141]
	s_add_u32 s28, s35, s48
	v_mad_i32_i24 v3, s27, v169, v3
	s_addc_u32 s29, s42, 0
	v_lshl_add_u64 v[2:3], s[28:29], 1, v[2:3]
	v_lshl_add_u64 v[2:3], v[2:3], 0, v[144:145]
	global_load_dwordx4 v[112:115], v[2:3], off offset:3168
	global_load_dwordx4 v[116:119], v[2:3], off offset:3136
	global_load_dwordx4 v[120:123], v[2:3], off offset:3104
	global_load_dwordx4 v[124:127], v[2:3], off offset:3072
	s_mul_hi_i32 s31, s6, 0x6000000
	s_mul_i32 s50, s6, 0x6000000
	s_lshl_b32 s6, s24, 1
	s_add_u32 s24, s12, s50
	v_add_u32_e32 v146, s25, v168
	s_addc_u32 s25, s13, s31
	s_lshl_b32 s22, s22, 8
	v_readfirstlane_b32 s30, v170
	s_add_u32 s24, s24, s22
	s_addc_u32 s25, s25, 0
	s_lshl_b32 s50, s30, 10
	s_mov_b32 s30, m0
	s_mov_b32 m0, s50
	s_nop 0
	global_load_lds_dwordx4 v156, s[24:25]
	s_mov_b32 m0, s30
	s_add_i32 s51, s50, 0x2000
	s_mov_b32 s30, m0
	s_mov_b32 m0, s51
	s_nop 0
	global_load_lds_dwordx4 v159, s[24:25]
	s_mov_b32 m0, s30
	v_readfirstlane_b32 s9, v171
	s_mov_b32 s31, m0
	s_mov_b32 m0, s9
	s_nop 0
	global_load_lds_dwordx4 v157, s[24:25]
	s_mov_b32 m0, s31
	v_readfirstlane_b32 s10, v172
	s_add_u32 s30, s24, 0x60000
	s_mov_b32 s58, m0
	s_mov_b32 m0, s10
	s_nop 0
	global_load_lds_dwordx4 v158, s[24:25]
	s_mov_b32 m0, s58
	s_addc_u32 s31, s25, 0
	s_add_i32 s54, s50, 0x8000
	s_mov_b32 s58, m0
	s_mov_b32 m0, s54
	s_nop 0
	global_load_lds_dwordx4 v156, s[30:31]
	s_mov_b32 m0, s58
	s_add_i32 s55, s50, 0xa000
	s_mov_b32 s54, m0
	s_mov_b32 m0, s55
	s_nop 0
	global_load_lds_dwordx4 v159, s[30:31]
	s_mov_b32 m0, s54
	s_add_i32 s56, s9, 0x8000
	s_mov_b32 s54, m0
	s_mov_b32 m0, s56
	s_nop 0
	global_load_lds_dwordx4 v157, s[30:31]
	s_mov_b32 m0, s54
	v_mov_b32_e32 v14, v0
	v_mov_b32_e32 v15, v0
	s_add_i32 s57, s10, 0x8000
	s_mov_b32 s54, m0
	s_mov_b32 m0, s57
	s_nop 0
	global_load_lds_dwordx4 v158, s[30:31]
	s_mov_b32 m0, s54
	v_mov_b32_e32 v1, v0
	v_mov_b32_e32 v2, v0
	v_mov_b32_e32 v3, v0
	v_mov_b32_e32 v4, v0
	v_mov_b32_e32 v5, v0
	v_mov_b32_e32 v6, v0
	v_mov_b32_e32 v7, v0
	v_mov_b32_e32 v8, v0
	v_mov_b32_e32 v9, v0
	v_mov_b32_e32 v10, v0
	v_mov_b32_e32 v11, v0
	v_mov_b32_e32 v12, v0
	v_mov_b32_e32 v13, v0
	v_mov_b64_e32 v[30:31], v[14:15]
	v_mov_b64_e32 v[46:47], v[14:15]
	v_mov_b64_e32 v[62:63], v[14:15]
	v_mov_b64_e32 v[78:79], v[14:15]
	s_mov_b32 s8, 63
	s_mov_b32 s11, 0
	v_mov_b32_e32 v143, 0
	v_mov_b32_e32 v147, 0xff800000
	v_mov_b64_e32 v[28:29], v[12:13]
	v_mov_b64_e32 v[26:27], v[10:11]
	v_mov_b64_e32 v[24:25], v[8:9]
	v_mov_b64_e32 v[22:23], v[6:7]
	v_mov_b64_e32 v[20:21], v[4:5]
	v_mov_b64_e32 v[18:19], v[2:3]
	v_mov_b64_e32 v[16:17], v[0:1]
	v_mov_b32_e32 v155, s27
	s_or_b32 s52, s6, 1
	s_or_b32 s53, s7, 31
	v_mov_b64_e32 v[44:45], v[12:13]
	v_mov_b64_e32 v[42:43], v[10:11]
	v_mov_b64_e32 v[40:41], v[8:9]
	v_mov_b64_e32 v[38:39], v[6:7]
	v_mov_b64_e32 v[36:37], v[4:5]
	v_mov_b64_e32 v[34:35], v[2:3]
	v_mov_b64_e32 v[32:33], v[0:1]
	v_mov_b64_e32 v[60:61], v[12:13]
	v_mov_b64_e32 v[58:59], v[10:11]
	v_mov_b64_e32 v[56:57], v[8:9]
	s_waitcnt vmcnt(0)
	s_waitcnt vmcnt(4) lgkmcnt(0)
	s_barrier
	v_mov_b64_e32 v[54:55], v[6:7]
	v_mov_b64_e32 v[52:53], v[4:5]
	v_mov_b64_e32 v[50:51], v[2:3]
	v_mov_b64_e32 v[48:49], v[0:1]
	s_mov_b32 s54, 0
	v_mov_b64_e32 v[76:77], v[12:13]
	v_mov_b64_e32 v[74:75], v[10:11]
	v_mov_b64_e32 v[72:73], v[8:9]
	v_mov_b64_e32 v[70:71], v[6:7]
	v_mov_b64_e32 v[68:69], v[4:5]
	v_mov_b64_e32 v[66:67], v[2:3]
	v_mov_b64_e32 v[64:65], v[0:1]
	s_mov_b32 s60, 0
	s_mov_b32 s61, 0
	v_mov_b32_e32 v240, 0
	v_mov_b32_e32 v241, 0
	v_mov_b32_e32 v242, 0
	v_mov_b32_e32 v243, 0
	v_mov_b32_e32 v244, 0
	v_mov_b32_e32 v245, 0
	v_mov_b32_e32 v246, 0
	v_mov_b32_e32 v247, 0
	v_mov_b32_e32 v248, 0
	v_mov_b32_e32 v249, 0
	v_mov_b32_e32 v250, 0
	v_mov_b32_e32 v251, 0
	v_mov_b32_e32 v252, 0
	v_mov_b32_e32 v253, 0
	v_mov_b32_e32 v254, 0
	v_mov_b32_e32 v255, 0
.Ldf1_loop:
	s_add_i32 s55, s54, 2
	s_cmp_lt_u32 s54, s6
	s_cselect_b32 s56, s55, s52
	s_lshl_b32 s57, s56, 6
	s_mul_i32 s56, s56, 0x60000
	s_mul_hi_u32 s57, s57, 0x1800
	s_add_u32 s56, s24, s56
	s_addc_u32 s57, s25, s57
	s_lshl_b32 s55, s55, 15
	s_and_b32 s55, s55, 0x18000
	s_add_i32 s58, s55, s50
	s_mov_b32 s59, m0
	s_mov_b32 m0, s58
	s_nop 0
	global_load_lds_dwordx4 v156, s[56:57]
	s_mov_b32 m0, s59
	s_add_i32 s58, s55, s51
	s_mov_b32 s59, m0
	s_mov_b32 m0, s58
	s_nop 0
	global_load_lds_dwordx4 v159, s[56:57]
	s_mov_b32 m0, s59
	s_add_i32 s58, s55, s9
	s_mov_b32 s59, m0
	s_mov_b32 m0, s58
	s_nop 0
	global_load_lds_dwordx4 v157, s[56:57]
	s_mov_b32 m0, s59
	s_add_i32 s55, s55, s10
	s_sub_i32 s58, s8, 63
	s_cmp_gt_u32 s58, s53
	s_mov_b32 s58, m0
	s_mov_b32 m0, s55
	s_nop 0
	global_load_lds_dwordx4 v158, s[56:57]
	s_mov_b32 m0, s58
	s_cbranch_scc1 .Ldf1_skip
	s_and_b32 s55, s11, 0x18000
	v_add_u32_e32 v2, s55, v160
	v_add_u32_e32 v3, v2, v161
	v_add_u32_e32 v4, v2, v162
	v_add_u32_e32 v5, v2, v163
	v_add_u32_e32 v2, v2, v164
	ds_read_b128 v[208:211], v3
	ds_read_b128 v[212:215], v3 offset:4096
	ds_read_b128 v[216:219], v4
	ds_read_b128 v[220:223], v4 offset:4096
	ds_read_b128 v[224:227], v5
	ds_read_b128 v[228:231], v5 offset:4096
	ds_read_b128 v[232:235], v2
	ds_read_b128 v[236:239], v2 offset:4096
	s_add_i32 s56, s11, 0x18000
	s_cmp_eq_u32 s61, 0
	s_cselect_b32 s56, s11, s56
	s_and_b32 s56, s56, 0x18000
	v_add_u32_e32 v6, s56, v165
	s_cmp_eq_u32 s60, 0
	s_cbranch_scc1 .Ldf1s_noresc
; DI f32x16 mfma32(bf16x8 a, bf16x8 b, f32x16 c) { return __builtin_amdgcn_mfma_f32_32x32x16_bf16(a, b, c, 0, 0, 0); }
; #define DF_VLD(VF, VOFF, H) do { _Pragma("unroll") for (int d2 = 0; d2 < 2; ++d2) { LAS unsigned char* vb_ = lds3 + (VOFF) + (2 * (H) + d2) * 4096; VF[2 * d2] = vfrag(vb_); VF[2 * d2 + 1] = vfrag(vb_ + 1024); } } while (0)
; #define DF_PVM(VF, P0, P1, H) do { _Pragma("unroll") for (int d2 = 0; d2 < 2; ++d2) { o[2 * (H) + d2] = mfma32(VF[2 * d2], P0, o[2 * (H) + d2]); o[2 * (H) + d2] = mfma32(VF[2 * d2 + 1], P1, o[2 * (H) + d2]); } } while (0)
; DI void diff_stage(const unsigned char* lds, LAS unsigned char* lds3, int buf, int t, int comp, int q0, int r32, int hi, int vlane, bool skew,
;                    const bf16x8 (&qf)[4], f32x16 (&o)[4], float& m, float& l, bf16x8 (&pp)[4], int& pvo, bool& have_prev) {
;     ...
;     if (skew && have_prev) {
; #pragma unroll
;         for (int sub = 0; sub < 2; ++sub) { DF_VLD(vf, pvo + sub * 2048, 0); DF_PVM(vf, pp[2 * sub], pp[2 * sub + 1], 0); DF_VLD(vf, pvo + sub * 2048, 1); DF_PVM(vf, pp[2 * sub], pp[2 * sub + 1], 1); }
;     }
;     f32x16 s0, s1;
; #pragma unroll
;     for (int i = 0; i < 16; ++i) { s0[i] = 0.f; s1[i] = 0.f; }
;     {
;         bf16x8 k0f[4], k1f[4];
; #pragma unroll
;         for (int c = 0; c < 4; ++c) { k0f[c] = *(const bf16x8*)(sb + ((32 * c) ^ ke16)); k1f[c] = *(const bf16x8*)(sb + 32 * 128 + ((32 * c) ^ ke16)); }
; #pragma unroll
;         for (int c = 0; c < 4; ++c) { s0 = mfma32(k0f[c], qf[c], s0); s1 = mfma32(k1f[c], qf[c], s1); }
;     }
;     if (k0 + 63 > q0) {
;         const int dq = q0 + r32 - k0 - 4 * hi;
; #pragma unroll
;         for (int i = 0; i < 16; ++i) { const int ci = (i & 3) + 8 * (i >> 2); s0[i] = (ci > dq) ? -INFINITY : s0[i]; s1[i] = (ci + 32 > dq) ? -INFINITY : s1[i]; }
	v_pk_mul_f32 v[78:79], v[78:79], v[206:207] op_sel_hi:[1,0]
	v_pk_mul_f32 v[76:77], v[76:77], v[206:207] op_sel_hi:[1,0]
	v_pk_mul_f32 v[74:75], v[74:75], v[206:207] op_sel_hi:[1,0]
	v_pk_mul_f32 v[72:73], v[72:73], v[206:207] op_sel_hi:[1,0]
	v_pk_mul_f32 v[70:71], v[70:71], v[206:207] op_sel_hi:[1,0]
	v_pk_mul_f32 v[68:69], v[68:69], v[206:207] op_sel_hi:[1,0]
	v_pk_mul_f32 v[66:67], v[66:67], v[206:207] op_sel_hi:[1,0]
	v_pk_mul_f32 v[64:65], v[64:65], v[206:207] op_sel_hi:[1,0]
	v_pk_mul_f32 v[62:63], v[62:63], v[206:207] op_sel_hi:[1,0]
	v_pk_mul_f32 v[60:61], v[60:61], v[206:207] op_sel_hi:[1,0]
	v_pk_mul_f32 v[58:59], v[58:59], v[206:207] op_sel_hi:[1,0]
	v_pk_mul_f32 v[56:57], v[56:57], v[206:207] op_sel_hi:[1,0]
	v_pk_mul_f32 v[54:55], v[54:55], v[206:207] op_sel_hi:[1,0]
	v_pk_mul_f32 v[52:53], v[52:53], v[206:207] op_sel_hi:[1,0]
	v_pk_mul_f32 v[50:51], v[50:51], v[206:207] op_sel_hi:[1,0]
	v_pk_mul_f32 v[48:49], v[48:49], v[206:207] op_sel_hi:[1,0]
	v_pk_mul_f32 v[46:47], v[46:47], v[206:207] op_sel_hi:[1,0]
	v_pk_mul_f32 v[44:45], v[44:45], v[206:207] op_sel_hi:[1,0]
	v_pk_mul_f32 v[42:43], v[42:43], v[206:207] op_sel_hi:[1,0]
	v_pk_mul_f32 v[40:41], v[40:41], v[206:207] op_sel_hi:[1,0]
	v_pk_mul_f32 v[38:39], v[38:39], v[206:207] op_sel_hi:[1,0]
	v_pk_mul_f32 v[36:37], v[36:37], v[206:207] op_sel_hi:[1,0]
	v_pk_mul_f32 v[34:35], v[34:35], v[206:207] op_sel_hi:[1,0]
	v_pk_mul_f32 v[32:33], v[32:33], v[206:207] op_sel_hi:[1,0]
	v_pk_mul_f32 v[30:31], v[30:31], v[206:207] op_sel_hi:[1,0]
	v_pk_mul_f32 v[28:29], v[28:29], v[206:207] op_sel_hi:[1,0]
	v_pk_mul_f32 v[26:27], v[26:27], v[206:207] op_sel_hi:[1,0]
	v_pk_mul_f32 v[24:25], v[24:25], v[206:207] op_sel_hi:[1,0]
	v_pk_mul_f32 v[22:23], v[22:23], v[206:207] op_sel_hi:[1,0]
	v_pk_mul_f32 v[20:21], v[20:21], v[206:207] op_sel_hi:[1,0]
	v_pk_mul_f32 v[18:19], v[18:19], v[206:207] op_sel_hi:[1,0]
	v_pk_mul_f32 v[16:17], v[16:17], v[206:207] op_sel_hi:[1,0]
	s_mov_b32 s60, 0
.Ldf1s_noresc:
	s_waitcnt lgkmcnt(7)
	v_mfma_f32_32x32x16_bf16 v[96:111], v[208:211], v[124:127], 0
	s_waitcnt lgkmcnt(6)
	v_mfma_f32_32x32x16_bf16 v[80:95], v[212:215], v[124:127], 0
	s_waitcnt lgkmcnt(5)
	v_mfma_f32_32x32x16_bf16 v[96:111], v[216:219], v[120:123], v[96:111]
	s_waitcnt lgkmcnt(4)
	v_mfma_f32_32x32x16_bf16 v[80:95], v[220:223], v[120:123], v[80:95]
	s_waitcnt lgkmcnt(3)
	v_mfma_f32_32x32x16_bf16 v[96:111], v[224:227], v[116:119], v[96:111]
	s_waitcnt lgkmcnt(2)
	v_mfma_f32_32x32x16_bf16 v[80:95], v[228:231], v[116:119], v[80:95]
	s_waitcnt lgkmcnt(1)
	v_mfma_f32_32x32x16_bf16 v[96:111], v[232:235], v[112:115], v[96:111]
	s_waitcnt lgkmcnt(0)
	v_mfma_f32_32x32x16_bf16 v[80:95], v[236:239], v[112:115], v[80:95]
	ds_read_b64_tr_b16 v[208:209], v6 offset:16384
	ds_read_b64_tr_b16 v[210:211], v6 offset:16896
	ds_read_b64_tr_b16 v[212:213], v6 offset:17408
	ds_read_b64_tr_b16 v[214:215], v6 offset:17920
	ds_read_b64_tr_b16 v[216:217], v6 offset:20480
	ds_read_b64_tr_b16 v[218:219], v6 offset:20992
	ds_read_b64_tr_b16 v[220:221], v6 offset:21504
	ds_read_b64_tr_b16 v[222:223], v6 offset:22016
	ds_read_b64_tr_b16 v[224:225], v6 offset:24576
	ds_read_b64_tr_b16 v[226:227], v6 offset:25088
	ds_read_b64_tr_b16 v[228:229], v6 offset:25600
	ds_read_b64_tr_b16 v[230:231], v6 offset:26112
	s_cmp_le_u32 s8, s7
	s_cbranch_scc1 .Ldf1_nodiag
	s_nop 7
	v_cmp_lt_i32_e32 vcc, -1, v146
	s_nop 1
	v_cndmask_b32_e32 v96, v176, v96, vcc
	v_cmp_lt_i32_e32 vcc, 31, v146
	s_nop 1
	v_cndmask_b32_e32 v80, v176, v80, vcc
	v_cmp_lt_i32_e32 vcc, 0, v146
	s_nop 1
	v_cndmask_b32_e32 v97, v176, v97, vcc
	v_cmp_lt_i32_e32 vcc, 32, v146
	s_nop 1
	v_cndmask_b32_e32 v81, v176, v81, vcc
	v_cmp_lt_i32_e32 vcc, 1, v146
	s_nop 1
	v_cndmask_b32_e32 v98, v176, v98, vcc
	v_cmp_lt_i32_e32 vcc, 33, v146
	s_nop 1
	v_cndmask_b32_e32 v82, v176, v82, vcc
	v_cmp_lt_i32_e32 vcc, 2, v146
	s_nop 1
	v_cndmask_b32_e32 v99, v176, v99, vcc
	v_cmp_lt_i32_e32 vcc, 34, v146
	s_nop 1
	v_cndmask_b32_e32 v83, v176, v83, vcc
	v_cmp_lt_i32_e32 vcc, 7, v146
	s_nop 1
	v_cndmask_b32_e32 v100, v176, v100, vcc
	v_cmp_lt_i32_e32 vcc, 39, v146
	s_nop 1
	v_cndmask_b32_e32 v84, v176, v84, vcc
	v_cmp_lt_i32_e32 vcc, 8, v146
	s_nop 1
	v_cndmask_b32_e32 v101, v176, v101, vcc
	v_cmp_lt_i32_e32 vcc, 40, v146
	s_nop 1
	v_cndmask_b32_e32 v85, v176, v85, vcc
	v_cmp_lt_i32_e32 vcc, 9, v146
	s_nop 1
	v_cndmask_b32_e32 v102, v176, v102, vcc
	v_cmp_lt_i32_e32 vcc, 41, v146
	s_nop 1
	v_cndmask_b32_e32 v86, v176, v86, vcc
	v_cmp_lt_i32_e32 vcc, 10, v146
	s_nop 1
	v_cndmask_b32_e32 v103, v176, v103, vcc
	v_cmp_lt_i32_e32 vcc, 42, v146
	s_nop 1
	v_cndmask_b32_e32 v87, v176, v87, vcc
	v_cmp_lt_i32_e32 vcc, 15, v146
	s_nop 1
	v_cndmask_b32_e32 v104, v176, v104, vcc
	v_cmp_lt_i32_e32 vcc, 47, v146
	s_nop 1
	v_cndmask_b32_e32 v88, v176, v88, vcc
	v_cmp_lt_i32_e32 vcc, 16, v146
	s_nop 1
	v_cndmask_b32_e32 v105, v176, v105, vcc
	v_cmp_lt_i32_e32 vcc, 48, v146
	s_nop 1
	v_cndmask_b32_e32 v89, v176, v89, vcc
	v_cmp_lt_i32_e32 vcc, 17, v146
	s_nop 1
	v_cndmask_b32_e32 v106, v176, v106, vcc
	v_cmp_lt_i32_e32 vcc, 49, v146
	s_nop 1
	v_cndmask_b32_e32 v90, v176, v90, vcc
	v_cmp_lt_i32_e32 vcc, 18, v146
	s_nop 1
	v_cndmask_b32_e32 v107, v176, v107, vcc
	v_cmp_lt_i32_e32 vcc, 50, v146
	s_nop 1
	v_cndmask_b32_e32 v91, v176, v91, vcc
	v_cmp_lt_i32_e32 vcc, 23, v146
	s_nop 1
	v_cndmask_b32_e32 v108, v176, v108, vcc
	v_cmp_lt_i32_e32 vcc, 55, v146
	s_nop 1
	v_cndmask_b32_e32 v92, v176, v92, vcc
	v_cmp_lt_i32_e32 vcc, 24, v146
	s_nop 1
	v_cndmask_b32_e32 v109, v176, v109, vcc
	v_cmp_lt_i32_e32 vcc, 56, v146
	s_nop 1
	v_cndmask_b32_e32 v93, v176, v93, vcc
	v_cmp_lt_i32_e32 vcc, 25, v146
	s_nop 1
	v_cndmask_b32_e32 v110, v176, v110, vcc
	v_cmp_lt_i32_e32 vcc, 57, v146
	s_nop 1
	v_cndmask_b32_e32 v94, v176, v94, vcc
	v_cmp_lt_i32_e32 vcc, 26, v146
	s_nop 1
	v_cndmask_b32_e32 v111, v176, v111, vcc
	v_cmp_lt_i32_e32 vcc, 58, v146
	s_nop 1
	v_cndmask_b32_e32 v95, v176, v95, vcc
; DI float xhalf(float v) { return __shfl_xor(v, 32); }
; DI float fexp2(float x) { return __builtin_amdgcn_exp2f(x); }
; #define DF_VLD(VF, VOFF, H) do { _Pragma("unroll") for (int d2 = 0; d2 < 2; ++d2) { LAS unsigned char* vb_ = lds3 + (VOFF) + (2 * (H) + d2) * 4096; VF[2 * d2] = vfrag(vb_); VF[2 * d2 + 1] = vfrag(vb_ + 1024); } } while (0)
; #define DF_PVM(VF, P0, P1, H) do { _Pragma("unroll") for (int d2 = 0; d2 < 2; ++d2) { o[2 * (H) + d2] = mfma32(VF[2 * d2], P0, o[2 * (H) + d2]); o[2 * (H) + d2] = mfma32(VF[2 * d2 + 1], P1, o[2 * (H) + d2]); } } while (0)
; DI void diff_stage(const unsigned char* lds, LAS unsigned char* lds3, int buf, int t, int comp, int q0, int r32, int hi, int vlane, bool skew,
;                    const bf16x8 (&qf)[4], f32x16 (&o)[4], float& m, float& l, bf16x8 (&pp)[4], int& pvo, bool& have_prev) {
;     ...
;     float mx = fmaxf(fmaxf(s0[0], s0[1]), s1[0]);
; #pragma unroll
;     for (int i = 1; i < 15; i += 2) { mx = fmaxf(fmaxf(mx, s0[i + 1]), s0[i + 2 > 15 ? 15 : i + 2]); mx = fmaxf(fmaxf(mx, s1[i]), s1[i + 1]); }
;     mx = fmaxf(mx, s1[15]);
;     mx = fmaxf(mx, xhalf(mx)) * SCL2;
;     if (__any(mx > m + 8.f)) {
;         const float mn = fmaxf(m, mx), al = fexp2(m - mn); l *= al; m = mn;
; #pragma unroll
;         for (int dt = 0; dt < 4; ++dt)
; #pragma unroll
;             for (int i = 0; i < 16; ++i) o[dt][i] *= al;
;     }
;     float sum0 = 0.f, sum1 = 0.f;
; #pragma unroll
;     for (int i = 0; i < 16; ++i) { s0[i] = fexp2(__builtin_fmaf(s0[i], SCL2, -m)); sum0 += s0[i]; s1[i] = fexp2(__builtin_fmaf(s1[i], SCL2, -m)); sum1 += s1[i]; }
;     l += sum0 + sum1;
;     const int vo = buf * DF_STAGE + DF_V + vlane;
;     if (!skew) {
;         const bf16x8 p00 = packP<0>(s0), p01 = packP<1>(s0);
;         DF_VLD(vf, vo, 0); DF_PVM(vf, p00, p01, 0); DF_VLD(vf, vo, 1); DF_PVM(vf, p00, p01, 1);
;         const bf16x8 p10 = packP<0>(s1), p11 = packP<1>(s1);
;         DF_VLD(vf, vo + 2048, 0); DF_PVM(vf, p10, p11, 0); DF_VLD(vf, vo + 2048, 1); DF_PVM(vf, p10, p11, 1);
;     } else { pp[0] = packP<0>(s0); pp[1] = packP<1>(s0); pp[2] = packP<0>(s1); pp[3] = packP<1>(s1); pvo = vo; have_prev = true; }
.Ldf1_nodiag:
	s_waitcnt lgkmcnt(10)
	v_mfma_f32_32x32x16_bf16 v[64:79], v[208:211], v[240:243], v[64:79]
	ds_read_b64_tr_b16 v[232:233], v6 offset:28672
	ds_read_b64_tr_b16 v[234:235], v6 offset:29184
	v_max3_f32 v1, v96, v97, v98
	v_max3_f32 v1, v1, v99, v100
	v_max3_f32 v1, v1, v101, v102
	v_max3_f32 v1, v1, v103, v104
	v_max3_f32 v1, v1, v105, v106
	v_max3_f32 v1, v1, v107, v108
	v_max3_f32 v1, v1, v109, v110
	v_max3_f32 v1, v1, v111, v80
	s_waitcnt lgkmcnt(10)
	v_mfma_f32_32x32x16_bf16 v[64:79], v[212:215], v[244:247], v[64:79]
	ds_read_b64_tr_b16 v[236:237], v6 offset:29696
	ds_read_b64_tr_b16 v[238:239], v6 offset:30208
	v_max3_f32 v1, v1, v81, v82
	v_max3_f32 v1, v1, v83, v84
	v_max3_f32 v1, v1, v85, v86
	v_max3_f32 v1, v1, v87, v88
	v_max3_f32 v1, v1, v89, v90
	v_max3_f32 v1, v1, v91, v92
	v_max3_f32 v1, v1, v93, v94
	v_max_f32_e32 v1, v1, v95
	s_waitcnt lgkmcnt(10)
	v_mfma_f32_32x32x16_bf16 v[48:63], v[216:219], v[240:243], v[48:63]
	ds_read_b64_tr_b16 v[208:209], v6 offset:18432
	ds_read_b64_tr_b16 v[210:211], v6 offset:18944
	v_mov_b32_e32 v14, v1
	s_nop 1
	v_permlane32_swap_b32_e32 v1, v14
	v_add_f32_e32 v15, 0x41000000, v147
	v_max_f32_e32 v1, v1, v14
	v_mul_f32_e32 v1, 0x3e38aa3b, v1
	v_cmp_gt_f32_e32 vcc, v1, v15
	s_cbranch_vccz .Ldf1_notrig
	v_max_f32_e32 v1, v1, v1
	v_max_f32_e32 v14, v147, v147
	v_max_f32_e32 v1, v14, v1
	v_sub_f32_e32 v14, v147, v1
	v_exp_f32_e32 v206, v14
	v_mov_b32_e32 v147, v1
	s_mov_b32 s60, 1
	v_mul_f32_e32 v143, v143, v206
.Ldf1_notrig:
	s_waitcnt lgkmcnt(10)
	v_mfma_f32_32x32x16_bf16 v[48:63], v[220:223], v[244:247], v[48:63]
	ds_read_b64_tr_b16 v[212:213], v6 offset:19456
	ds_read_b64_tr_b16 v[214:215], v6 offset:19968
	v_fma_f32 v96, v96, s44, -v147
	v_fma_f32 v97, v97, s44, -v147
	v_exp_f32_e32 v96, v96
	v_exp_f32_e32 v97, v97
	v_fma_f32 v98, v98, s44, -v147
	v_fma_f32 v99, v99, s44, -v147
	v_exp_f32_e32 v98, v98
	v_exp_f32_e32 v99, v99
	s_waitcnt lgkmcnt(10)
	v_mfma_f32_32x32x16_bf16 v[32:47], v[224:227], v[240:243], v[32:47]
	ds_read_b64_tr_b16 v[216:217], v6 offset:22528
	ds_read_b64_tr_b16 v[218:219], v6 offset:23040
	v_fma_f32 v100, v100, s44, -v147
	v_fma_f32 v101, v101, s44, -v147
	v_exp_f32_e32 v100, v100
	v_exp_f32_e32 v101, v101
	v_fma_f32 v102, v102, s44, -v147
	v_fma_f32 v103, v103, s44, -v147
	v_exp_f32_e32 v102, v102
	v_exp_f32_e32 v103, v103
	s_waitcnt lgkmcnt(10)
	v_mfma_f32_32x32x16_bf16 v[32:47], v[228:231], v[244:247], v[32:47]
	ds_read_b64_tr_b16 v[220:221], v6 offset:23552
	ds_read_b64_tr_b16 v[222:223], v6 offset:24064
	v_fma_f32 v104, v104, s44, -v147
	v_fma_f32 v105, v105, s44, -v147
	v_exp_f32_e32 v104, v104
	v_exp_f32_e32 v105, v105
	v_fma_f32 v106, v106, s44, -v147
	v_fma_f32 v107, v107, s44, -v147
	v_exp_f32_e32 v106, v106
	v_exp_f32_e32 v107, v107
	s_waitcnt lgkmcnt(10)
	v_mfma_f32_32x32x16_bf16 v[16:31], v[232:235], v[240:243], v[16:31]
	ds_read_b64_tr_b16 v[224:225], v6 offset:26624
	ds_read_b64_tr_b16 v[226:227], v6 offset:27136
	v_fma_f32 v108, v108, s44, -v147
	v_fma_f32 v109, v109, s44, -v147
	v_exp_f32_e32 v108, v108
	v_exp_f32_e32 v109, v109
	v_fma_f32 v110, v110, s44, -v147
	v_fma_f32 v111, v111, s44, -v147
	v_exp_f32_e32 v110, v110
	v_exp_f32_e32 v111, v111
	s_waitcnt lgkmcnt(10)
	v_mfma_f32_32x32x16_bf16 v[16:31], v[236:239], v[244:247], v[16:31]
	ds_read_b64_tr_b16 v[228:229], v6 offset:27648
	ds_read_b64_tr_b16 v[230:231], v6 offset:28160
	v_add_f32_e32 v14, v96, v97
	v_add_f32_e32 v14, v14, v98
	v_add_f32_e32 v14, v14, v99
	v_add_f32_e32 v14, v14, v100
	v_add_f32_e32 v14, v14, v101
	v_add_f32_e32 v14, v14, v102
	v_add_f32_e32 v14, v14, v103
	v_add_f32_e32 v14, v14, v104
	s_waitcnt lgkmcnt(10)
	v_mfma_f32_32x32x16_bf16 v[64:79], v[208:211], v[248:251], v[64:79]
	ds_read_b64_tr_b16 v[232:233], v6 offset:30720
	ds_read_b64_tr_b16 v[234:235], v6 offset:31232
	v_cvt_pk_bf16_f32 v240, v96, v97
	v_cvt_pk_bf16_f32 v241, v98, v99
	v_cvt_pk_bf16_f32 v242, v100, v101
	v_cvt_pk_bf16_f32 v243, v102, v103
	v_cvt_pk_bf16_f32 v244, v104, v105
	v_cvt_pk_bf16_f32 v245, v106, v107
	v_cvt_pk_bf16_f32 v246, v108, v109
	v_cvt_pk_bf16_f32 v247, v110, v111
	s_waitcnt lgkmcnt(10)
	v_mfma_f32_32x32x16_bf16 v[64:79], v[212:215], v[252:255], v[64:79]
	ds_read_b64_tr_b16 v[236:237], v6 offset:31744
	ds_read_b64_tr_b16 v[238:239], v6 offset:32256
	v_add_f32_e32 v14, v14, v105
	v_add_f32_e32 v14, v14, v106
	v_add_f32_e32 v14, v14, v107
	v_add_f32_e32 v14, v14, v108
	v_add_f32_e32 v14, v14, v109
	v_add_f32_e32 v14, v14, v110
	v_add_f32_e32 v14, v14, v111
	v_fma_f32 v80, v80, s44, -v147
	s_waitcnt lgkmcnt(10)
	v_mfma_f32_32x32x16_bf16 v[48:63], v[216:219], v[248:251], v[48:63]
	v_fma_f32 v81, v81, s44, -v147
	v_exp_f32_e32 v80, v80
	v_exp_f32_e32 v81, v81
	v_fma_f32 v82, v82, s44, -v147
	v_fma_f32 v83, v83, s44, -v147
	v_exp_f32_e32 v82, v82
	v_exp_f32_e32 v83, v83
	v_fma_f32 v84, v84, s44, -v147
	s_waitcnt lgkmcnt(8)
	v_mfma_f32_32x32x16_bf16 v[48:63], v[220:223], v[252:255], v[48:63]
	v_fma_f32 v85, v85, s44, -v147
	v_exp_f32_e32 v84, v84
	v_exp_f32_e32 v85, v85
	v_fma_f32 v86, v86, s44, -v147
	v_fma_f32 v87, v87, s44, -v147
	v_exp_f32_e32 v86, v86
	v_exp_f32_e32 v87, v87
	v_fma_f32 v88, v88, s44, -v147
	s_waitcnt lgkmcnt(6)
	v_mfma_f32_32x32x16_bf16 v[32:47], v[224:227], v[248:251], v[32:47]
	v_fma_f32 v89, v89, s44, -v147
	v_exp_f32_e32 v88, v88
	v_exp_f32_e32 v89, v89
	v_fma_f32 v90, v90, s44, -v147
	v_fma_f32 v91, v91, s44, -v147
	v_exp_f32_e32 v90, v90
	v_exp_f32_e32 v91, v91
	v_fma_f32 v92, v92, s44, -v147
	s_waitcnt lgkmcnt(4)
	v_mfma_f32_32x32x16_bf16 v[32:47], v[228:231], v[252:255], v[32:47]
	v_fma_f32 v93, v93, s44, -v147
	v_exp_f32_e32 v92, v92
	v_exp_f32_e32 v93, v93
	v_fma_f32 v94, v94, s44, -v147
	v_fma_f32 v95, v95, s44, -v147
	v_exp_f32_e32 v94, v94
	v_exp_f32_e32 v95, v95
	v_add_f32_e32 v15, v80, v81
	s_waitcnt lgkmcnt(2)
	v_mfma_f32_32x32x16_bf16 v[16:31], v[232:235], v[248:251], v[16:31]
	v_add_f32_e32 v15, v15, v82
	v_add_f32_e32 v15, v15, v83
	v_add_f32_e32 v15, v15, v84
	v_add_f32_e32 v15, v15, v85
	v_add_f32_e32 v15, v15, v86
	v_add_f32_e32 v15, v15, v87
	v_add_f32_e32 v15, v15, v88
	v_add_f32_e32 v15, v15, v89
	s_waitcnt lgkmcnt(0)
	v_mfma_f32_32x32x16_bf16 v[16:31], v[236:239], v[252:255], v[16:31]
	v_add_f32_e32 v15, v15, v90
	v_add_f32_e32 v15, v15, v91
	v_add_f32_e32 v15, v15, v92
	v_add_f32_e32 v15, v15, v93
	v_add_f32_e32 v15, v15, v94
	v_add_f32_e32 v15, v15, v95
	v_add_f32_e32 v14, v14, v15
	v_add_f32_e32 v143, v143, v14
	v_cvt_pk_bf16_f32 v248, v80, v81
	v_cvt_pk_bf16_f32 v249, v82, v83
	v_cvt_pk_bf16_f32 v250, v84, v85
	v_cvt_pk_bf16_f32 v251, v86, v87
	v_cvt_pk_bf16_f32 v252, v88, v89
	v_cvt_pk_bf16_f32 v253, v90, v91
	v_cvt_pk_bf16_f32 v254, v92, v93
	v_cvt_pk_bf16_f32 v255, v94, v95
	s_mov_b32 s61, 1
	s_branch .Ldf1_bar
; #define DF_VLD(VF, VOFF, H) do { _Pragma("unroll") for (int d2 = 0; d2 < 2; ++d2) { LAS unsigned char* vb_ = lds3 + (VOFF) + (2 * (H) + d2) * 4096; VF[2 * d2] = vfrag(vb_); VF[2 * d2 + 1] = vfrag(vb_ + 1024); } } while (0)
; #define DF_PVM(VF, P0, P1, H) do { _Pragma("unroll") for (int d2 = 0; d2 < 2; ++d2) { o[2 * (H) + d2] = mfma32(VF[2 * d2], P0, o[2 * (H) + d2]); o[2 * (H) + d2] = mfma32(VF[2 * d2 + 1], P1, o[2 * (H) + d2]); } } while (0)
; #define DF_DMA(t, bufi) do { const bf16_t* sb_ = sbase + (size_t)(64 * (t)) * QKVW; const unsigned base_ = (unsigned)__builtin_amdgcn_readfirstlane(ldsb + (bufi) * DF_STAGE); \
;         glds16s(sb_, oK, base_ + dK); glds16s(sb_, oK + 128u, base_ + DF_K2 + dK); glds16s(sb_, oV0, base_ + dV0); glds16s(sb_, oV1, base_ + dV1); } while (0)
; #define DF_WAITBAR(N) asm volatile("s_waitcnt vmcnt(" #N ") lgkmcnt(0)\n\ts_barrier" ::: "memory")
; DI void diff_stage(const unsigned char* lds, LAS unsigned char* lds3, int buf, int t, int comp, int q0, int r32, int hi, int vlane, bool skew,
;                    const bf16x8 (&qf)[4], f32x16 (&o)[4], float& m, float& l, bf16x8 (&pp)[4], int& pvo, bool& have_prev) {
;     ...
;     if (skew && have_prev) {
; #pragma unroll
;         for (int sub = 0; sub < 2; ++sub) { DF_VLD(vf, pvo + sub * 2048, 0); DF_PVM(vf, pp[2 * sub], pp[2 * sub + 1], 0); DF_VLD(vf, pvo + sub * 2048, 1); DF_PVM(vf, pp[2 * sub], pp[2 * sub + 1], 1); }
;     }
; DI void diff_unit(const Args& A, const bf16_t* QKV, bf16_t* ATT, unsigned char* lds, LAS unsigned char* lds3, int b, int head, int qb, int tid, int wid, int lane) {
;     ...
;     for (int t = 0; t < nst; ++t) {
;         { const int tl = (t + 2 < nst) ? t + 2 : nst - 1; DF_DMA(tl, (t + 2) & 3); }
;         diff_stage(lds, lds3, t & 3, t, comp, q0, r32, hi, vlane, skew, qf, o, m, l, pp, pvo, have_prev);
;         DF_WAITBAR(4);
.Ldf1_skip:
	s_cmp_eq_u32 s61, 0
	s_cbranch_scc1 .Ldf1_bar
	s_add_i32 s56, s11, 0x18000
	s_and_b32 s56, s56, 0x18000
	v_add_u32_e32 v6, s56, v165
	s_cmp_eq_u32 s60, 0
	s_cbranch_scc1 .Ldf1k_noresc
	v_pk_mul_f32 v[78:79], v[78:79], v[206:207] op_sel_hi:[1,0]
	v_pk_mul_f32 v[76:77], v[76:77], v[206:207] op_sel_hi:[1,0]
	v_pk_mul_f32 v[74:75], v[74:75], v[206:207] op_sel_hi:[1,0]
	v_pk_mul_f32 v[72:73], v[72:73], v[206:207] op_sel_hi:[1,0]
	v_pk_mul_f32 v[70:71], v[70:71], v[206:207] op_sel_hi:[1,0]
	v_pk_mul_f32 v[68:69], v[68:69], v[206:207] op_sel_hi:[1,0]
	v_pk_mul_f32 v[66:67], v[66:67], v[206:207] op_sel_hi:[1,0]
	v_pk_mul_f32 v[64:65], v[64:65], v[206:207] op_sel_hi:[1,0]
	v_pk_mul_f32 v[62:63], v[62:63], v[206:207] op_sel_hi:[1,0]
	v_pk_mul_f32 v[60:61], v[60:61], v[206:207] op_sel_hi:[1,0]
	v_pk_mul_f32 v[58:59], v[58:59], v[206:207] op_sel_hi:[1,0]
	v_pk_mul_f32 v[56:57], v[56:57], v[206:207] op_sel_hi:[1,0]
	v_pk_mul_f32 v[54:55], v[54:55], v[206:207] op_sel_hi:[1,0]
	v_pk_mul_f32 v[52:53], v[52:53], v[206:207] op_sel_hi:[1,0]
	v_pk_mul_f32 v[50:51], v[50:51], v[206:207] op_sel_hi:[1,0]
	v_pk_mul_f32 v[48:49], v[48:49], v[206:207] op_sel_hi:[1,0]
	v_pk_mul_f32 v[46:47], v[46:47], v[206:207] op_sel_hi:[1,0]
	v_pk_mul_f32 v[44:45], v[44:45], v[206:207] op_sel_hi:[1,0]
	v_pk_mul_f32 v[42:43], v[42:43], v[206:207] op_sel_hi:[1,0]
	v_pk_mul_f32 v[40:41], v[40:41], v[206:207] op_sel_hi:[1,0]
	v_pk_mul_f32 v[38:39], v[38:39], v[206:207] op_sel_hi:[1,0]
	v_pk_mul_f32 v[36:37], v[36:37], v[206:207] op_sel_hi:[1,0]
	v_pk_mul_f32 v[34:35], v[34:35], v[206:207] op_sel_hi:[1,0]
	v_pk_mul_f32 v[32:33], v[32:33], v[206:207] op_sel_hi:[1,0]
	v_pk_mul_f32 v[30:31], v[30:31], v[206:207] op_sel_hi:[1,0]
	v_pk_mul_f32 v[28:29], v[28:29], v[206:207] op_sel_hi:[1,0]
	v_pk_mul_f32 v[26:27], v[26:27], v[206:207] op_sel_hi:[1,0]
	v_pk_mul_f32 v[24:25], v[24:25], v[206:207] op_sel_hi:[1,0]
	v_pk_mul_f32 v[22:23], v[22:23], v[206:207] op_sel_hi:[1,0]
	v_pk_mul_f32 v[20:21], v[20:21], v[206:207] op_sel_hi:[1,0]
	v_pk_mul_f32 v[18:19], v[18:19], v[206:207] op_sel_hi:[1,0]
	v_pk_mul_f32 v[16:17], v[16:17], v[206:207] op_sel_hi:[1,0]
	s_mov_b32 s60, 0
.Ldf1k_noresc:
	ds_read_b64_tr_b16 v[208:209], v6 offset:16384
	ds_read_b64_tr_b16 v[210:211], v6 offset:16896
	ds_read_b64_tr_b16 v[212:213], v6 offset:17408
	ds_read_b64_tr_b16 v[214:215], v6 offset:17920
	ds_read_b64_tr_b16 v[216:217], v6 offset:20480
	ds_read_b64_tr_b16 v[218:219], v6 offset:20992
	ds_read_b64_tr_b16 v[220:221], v6 offset:21504
	ds_read_b64_tr_b16 v[222:223], v6 offset:22016
	ds_read_b64_tr_b16 v[224:225], v6 offset:24576
	ds_read_b64_tr_b16 v[226:227], v6 offset:25088
	ds_read_b64_tr_b16 v[228:229], v6 offset:25600
	ds_read_b64_tr_b16 v[230:231], v6 offset:26112
	s_waitcnt lgkmcnt(10)
	v_mfma_f32_32x32x16_bf16 v[64:79], v[208:211], v[240:243], v[64:79]
	ds_read_b64_tr_b16 v[232:233], v6 offset:28672
	ds_read_b64_tr_b16 v[234:235], v6 offset:29184
	s_waitcnt lgkmcnt(10)
	v_mfma_f32_32x32x16_bf16 v[64:79], v[212:215], v[244:247], v[64:79]
	ds_read_b64_tr_b16 v[236:237], v6 offset:29696
	ds_read_b64_tr_b16 v[238:239], v6 offset:30208
	s_waitcnt lgkmcnt(10)
	v_mfma_f32_32x32x16_bf16 v[48:63], v[216:219], v[240:243], v[48:63]
	ds_read_b64_tr_b16 v[208:209], v6 offset:18432
	ds_read_b64_tr_b16 v[210:211], v6 offset:18944
	s_waitcnt lgkmcnt(10)
	v_mfma_f32_32x32x16_bf16 v[48:63], v[220:223], v[244:247], v[48:63]
	ds_read_b64_tr_b16 v[212:213], v6 offset:19456
	ds_read_b64_tr_b16 v[214:215], v6 offset:19968
	s_waitcnt lgkmcnt(10)
	v_mfma_f32_32x32x16_bf16 v[32:47], v[224:227], v[240:243], v[32:47]
	ds_read_b64_tr_b16 v[216:217], v6 offset:22528
	ds_read_b64_tr_b16 v[218:219], v6 offset:23040
	s_waitcnt lgkmcnt(10)
	v_mfma_f32_32x32x16_bf16 v[32:47], v[228:231], v[244:247], v[32:47]
	ds_read_b64_tr_b16 v[220:221], v6 offset:23552
	ds_read_b64_tr_b16 v[222:223], v6 offset:24064
	s_waitcnt lgkmcnt(10)
	v_mfma_f32_32x32x16_bf16 v[16:31], v[232:235], v[240:243], v[16:31]
	ds_read_b64_tr_b16 v[224:225], v6 offset:26624
	ds_read_b64_tr_b16 v[226:227], v6 offset:27136
	s_waitcnt lgkmcnt(10)
	v_mfma_f32_32x32x16_bf16 v[16:31], v[236:239], v[244:247], v[16:31]
	ds_read_b64_tr_b16 v[228:229], v6 offset:27648
	ds_read_b64_tr_b16 v[230:231], v6 offset:28160
	s_waitcnt lgkmcnt(10)
	v_mfma_f32_32x32x16_bf16 v[64:79], v[208:211], v[248:251], v[64:79]
	ds_read_b64_tr_b16 v[232:233], v6 offset:30720
	ds_read_b64_tr_b16 v[234:235], v6 offset:31232
	s_waitcnt lgkmcnt(10)
	v_mfma_f32_32x32x16_bf16 v[64:79], v[212:215], v[252:255], v[64:79]
	ds_read_b64_tr_b16 v[236:237], v6 offset:31744
	ds_read_b64_tr_b16 v[238:239], v6 offset:32256
	s_waitcnt lgkmcnt(10)
	v_mfma_f32_32x32x16_bf16 v[48:63], v[216:219], v[248:251], v[48:63]
	s_waitcnt lgkmcnt(8)
	v_mfma_f32_32x32x16_bf16 v[48:63], v[220:223], v[252:255], v[48:63]
	s_waitcnt lgkmcnt(6)
	v_mfma_f32_32x32x16_bf16 v[32:47], v[224:227], v[248:251], v[32:47]
	s_waitcnt lgkmcnt(4)
	v_mfma_f32_32x32x16_bf16 v[32:47], v[228:231], v[252:255], v[32:47]
	s_waitcnt lgkmcnt(2)
	v_mfma_f32_32x32x16_bf16 v[16:31], v[232:235], v[248:251], v[16:31]
	s_waitcnt lgkmcnt(0)
	v_mfma_f32_32x32x16_bf16 v[16:31], v[236:239], v[252:255], v[16:31]
	s_mov_b32 s61, 0

; #define DF_VLD(VF, VOFF, H) do { _Pragma("unroll") for (int d2 = 0; d2 < 2; ++d2) { LAS unsigned char* vb_ = lds3 + (VOFF) + (2 * (H) + d2) * 4096; VF[2 * d2] = vfrag(vb_); VF[2 * d2 + 1] = vfrag(vb_ + 1024); } } while (0)
; #define DF_PVM(VF, P0, P1, H) do { _Pragma("unroll") for (int d2 = 0; d2 < 2; ++d2) { o[2 * (H) + d2] = mfma32(VF[2 * d2], P0, o[2 * (H) + d2]); o[2 * (H) + d2] = mfma32(VF[2 * d2 + 1], P1, o[2 * (H) + d2]); } } while (0)
; DI void diff_unit(const Args& A, const bf16_t* QKV, bf16_t* ATT, unsigned char* lds, LAS unsigned char* lds3, int b, int head, int qb, int tid, int wid, int lane) {
;     ...
;     asm volatile("s_waitcnt vmcnt(0)" ::: "memory");
;     ...
;     if (skew && have_prev) { bf16x8 vf[4];
; #pragma unroll
;         for (int sub = 0; sub < 2; ++sub) { DF_VLD(vf, pvo + sub * 2048, 0); DF_PVM(vf, pp[2 * sub], pp[2 * sub + 1], 0); DF_VLD(vf, pvo + sub * 2048, 1); DF_PVM(vf, pp[2 * sub], pp[2 * sub + 1], 1); } }
.Ldf1x_noresc:
	ds_read_b64_tr_b16 v[208:209], v6 offset:16384
	ds_read_b64_tr_b16 v[210:211], v6 offset:16896
	ds_read_b64_tr_b16 v[212:213], v6 offset:17408
	ds_read_b64_tr_b16 v[214:215], v6 offset:17920
	ds_read_b64_tr_b16 v[216:217], v6 offset:20480
	ds_read_b64_tr_b16 v[218:219], v6 offset:20992
	ds_read_b64_tr_b16 v[220:221], v6 offset:21504
	ds_read_b64_tr_b16 v[222:223], v6 offset:22016
	ds_read_b64_tr_b16 v[224:225], v6 offset:24576
	ds_read_b64_tr_b16 v[226:227], v6 offset:25088
	ds_read_b64_tr_b16 v[228:229], v6 offset:25600
	ds_read_b64_tr_b16 v[230:231], v6 offset:26112
	s_waitcnt lgkmcnt(10)
	v_mfma_f32_32x32x16_bf16 v[64:79], v[208:211], v[240:243], v[64:79]
	ds_read_b64_tr_b16 v[232:233], v6 offset:28672
	ds_read_b64_tr_b16 v[234:235], v6 offset:29184
	s_waitcnt lgkmcnt(10)
	v_mfma_f32_32x32x16_bf16 v[64:79], v[212:215], v[244:247], v[64:79]
	ds_read_b64_tr_b16 v[236:237], v6 offset:29696
	ds_read_b64_tr_b16 v[238:239], v6 offset:30208
	s_waitcnt lgkmcnt(10)
	v_mfma_f32_32x32x16_bf16 v[48:63], v[216:219], v[240:243], v[48:63]
	ds_read_b64_tr_b16 v[208:209], v6 offset:18432
	ds_read_b64_tr_b16 v[210:211], v6 offset:18944
	s_waitcnt lgkmcnt(10)
	v_mfma_f32_32x32x16_bf16 v[48:63], v[220:223], v[244:247], v[48:63]
	ds_read_b64_tr_b16 v[212:213], v6 offset:19456
	ds_read_b64_tr_b16 v[214:215], v6 offset:19968
	s_waitcnt lgkmcnt(10)
	v_mfma_f32_32x32x16_bf16 v[32:47], v[224:227], v[240:243], v[32:47]
	ds_read_b64_tr_b16 v[216:217], v6 offset:22528
	ds_read_b64_tr_b16 v[218:219], v6 offset:23040
	s_waitcnt lgkmcnt(10)
	v_mfma_f32_32x32x16_bf16 v[32:47], v[228:231], v[244:247], v[32:47]
	ds_read_b64_tr_b16 v[220:221], v6 offset:23552
	ds_read_b64_tr_b16 v[222:223], v6 offset:24064
	s_waitcnt lgkmcnt(10)
	v_mfma_f32_32x32x16_bf16 v[16:31], v[232:235], v[240:243], v[16:31]
	ds_read_b64_tr_b16 v[224:225], v6 offset:26624
	ds_read_b64_tr_b16 v[226:227], v6 offset:27136
	s_waitcnt lgkmcnt(10)
	v_mfma_f32_32x32x16_bf16 v[16:31], v[236:239], v[244:247], v[16:31]
	ds_read_b64_tr_b16 v[228:229], v6 offset:27648
	ds_read_b64_tr_b16 v[230:231], v6 offset:28160
	s_waitcnt lgkmcnt(10)
	v_mfma_f32_32x32x16_bf16 v[64:79], v[208:211], v[248:251], v[64:79]
	ds_read_b64_tr_b16 v[232:233], v6 offset:30720
	ds_read_b64_tr_b16 v[234:235], v6 offset:31232
	s_waitcnt lgkmcnt(10)
	v_mfma_f32_32x32x16_bf16 v[64:79], v[212:215], v[252:255], v[64:79]
	ds_read_b64_tr_b16 v[236:237], v6 offset:31744
	ds_read_b64_tr_b16 v[238:239], v6 offset:32256
	s_waitcnt lgkmcnt(10)
	v_mfma_f32_32x32x16_bf16 v[48:63], v[216:219], v[248:251], v[48:63]
	s_waitcnt lgkmcnt(8)
	v_mfma_f32_32x32x16_bf16 v[48:63], v[220:223], v[252:255], v[48:63]
	s_waitcnt lgkmcnt(6)
	v_mfma_f32_32x32x16_bf16 v[32:47], v[224:227], v[248:251], v[32:47]
	s_waitcnt lgkmcnt(4)
	v_mfma_f32_32x32x16_bf16 v[32:47], v[228:231], v[252:255], v[32:47]
	s_waitcnt lgkmcnt(2)
	v_mfma_f32_32x32x16_bf16 v[16:31], v[232:235], v[248:251], v[16:31]
	s_waitcnt lgkmcnt(0)
	v_mfma_f32_32x32x16_bf16 v[16:31], v[236:239], v[252:255], v[16:31]
	s_branch .LBB0_287

; #define LAS __attribute__((address_space(3)))
; #define DF_WAITBAR(N) asm volatile("s_waitcnt vmcnt(" #N ") lgkmcnt(0)\n\ts_barrier" ::: "memory")
; DI void diff_unit(const Args& A, const bf16_t* QKV, bf16_t* ATT, unsigned char* lds, LAS unsigned char* lds3, int b, int head, int qb, int tid, int wid, int lane) {
;     const int r32 = lane & 31, hi = lane >> 5, comp = wid >> 2, wq = wid & 3;
;     const size_t rowbase = (size_t)b * SEQ;
;     const int q0 = qb * 128 + wq * 32;
;     const int qcol = 1536 + head * 128 + comp * 64;
;     bf16x8 qf[4];
; #pragma unroll
;     for (int c = 0; c < 4; ++c) qf[c] = *(const bf16x8*)(QKV + (rowbase + q0 + r32) * QKVW + qcol + 16 * c + 8 * hi);
;     f32x16 o[4];
; #pragma unroll
;     for (int t = 0; t < 4; ++t)
; #pragma unroll
;         for (int i = 0; i < 16; ++i) o[t][i] = 0.f;
;     float m = -INFINITY, l = 0.f;
;     const int nst = 2 * (qb + 1);
;     const unsigned ldsb = (unsigned)(uintptr_t)lds3;
;     const int kkey = 8 * wid + (lane >> 3), kch = (lane & 7) ^ ((kkey >> 1) & 7);
;     const int vi0 = 2 * wid, vi1 = 2 * wid + 1;
;     const bf16_t* sbase = QKV + rowbase * QKVW + head * 128;
;     const unsigned oK = (unsigned)((kkey * QKVW + 2048 + kch * 8) * 2);
;     const unsigned oV0 = (unsigned)(((16 * (vi0 & 3) + (lane >> 2)) * QKVW + 2560 + ((vi0 >> 2) * 4 + (lane & 3)) * 8) * 2);
;     const unsigned oV1 = (unsigned)(((16 * (vi1 & 3) + (lane >> 2)) * QKVW + 2560 + ((vi1 >> 2) * 4 + (lane & 3)) * 8) * 2);
;     const unsigned dK = (unsigned)__builtin_amdgcn_readfirstlane(wid * 1024);
;     const unsigned dV0 = (unsigned)__builtin_amdgcn_readfirstlane(DF_V + (vi0 >> 2) * 4096 + (vi0 & 3) * 1024), dV1 = (unsigned)__builtin_amdgcn_readfirstlane(DF_V + (vi1 >> 2) * 4096 + (vi1 & 3) * 1024);
;     ...
;     DF_DMA(0, 0); DF_DMA(1, 1);
;     asm volatile("" : "+v"(qf[0]), "+v"(qf[1]), "+v"(qf[2]), "+v"(qf[3]));
;     DF_WAITBAR(4);
;     const int vlane = (4 * hi + ((lane & 15) >> 2)) * 64 + ((lane >> 4) & 1) * 32 + (lane & 3) * 8;
;     const bool skew = false;
;     bf16x8 pp[4]; { const bf16x8 z8 = {0, 0, 0, 0, 0, 0, 0, 0}; pp[0] = z8; pp[1] = z8; pp[2] = z8; pp[3] = z8; } int pvo = vlane; bool have_prev = false;
;     for (int t = 0; t < nst; ++t) {
;         { const int tl = (t + 2 < nst) ? t + 2 : nst - 1; DF_DMA(tl, (t + 2) & 3); }
.LBB0_291:
	s_lshl_b32 s52, s49, 7
	s_or_b32 s10, s52, s34
	v_or_b32_e32 v1, s10, v129
	v_or_b32_e32 v154, s26, v1
	v_mov_b64_e32 v[2:3], s[12:13]
	v_mad_u64_u32 v[2:3], s[50:51], v154, s43, v[2:3]
	v_mad_i32_i24 v3, s27, v169, v3
	v_lshl_add_u64 v[2:3], s[28:29], 1, v[2:3]
	v_mov_b32_e32 v143, v0
	v_lshl_add_u64 v[2:3], v[2:3], 0, v[142:143]
	s_barrier
	global_load_dwordx4 v[112:115], v[2:3], off offset:3168
	global_load_dwordx4 v[116:119], v[2:3], off offset:3136
	global_load_dwordx4 v[120:123], v[2:3], off offset:3104
	global_load_dwordx4 v[124:127], v[2:3], off offset:3072
	s_lshl_b32 s22, s33, 10
	v_add_u32_e32 v183, s52, v168
	s_mov_b32 s52, m0
	s_mov_b32 m0, s22
	s_nop 0
	global_load_lds_dwordx4 v156, s[24:25]
	s_mov_b32 m0, s52
	s_add_i32 s28, s22, 0x2000
	s_mov_b32 s52, m0
	s_mov_b32 m0, s28
	s_nop 0
	global_load_lds_dwordx4 v159, s[24:25]
	s_mov_b32 m0, s52
	s_add_i32 s53, s22, 0x8000
	s_mov_b32 s52, m0
	s_mov_b32 m0, s36
	s_nop 0
	global_load_lds_dwordx4 v157, s[24:25]
	s_mov_b32 m0, s52
	s_add_i32 s54, s22, 0xa000
	s_mov_b32 s52, m0
	s_mov_b32 m0, s37
	s_nop 0
	global_load_lds_dwordx4 v158, s[24:25]
	s_mov_b32 m0, s52
	s_add_i32 s50, s36, 0x8000
	s_mov_b32 s52, m0
	s_mov_b32 m0, s53
	s_nop 0
	global_load_lds_dwordx4 v156, s[30:31]
	s_mov_b32 m0, s52
	s_add_i32 s51, s37, 0x8000
	s_mov_b32 s52, m0
	s_mov_b32 m0, s54
	s_nop 0
	global_load_lds_dwordx4 v159, s[30:31]
	s_mov_b32 m0, s52
	v_mov_b32_e32 v14, v0
	s_mov_b32 s52, m0
	s_mov_b32 m0, s50
	s_nop 0
	global_load_lds_dwordx4 v157, s[30:31]
	s_mov_b32 m0, s52
	v_mov_b32_e32 v15, v0
	s_mov_b32 s50, m0
	s_mov_b32 m0, s51
	s_nop 0
	global_load_lds_dwordx4 v158, s[30:31]
	s_mov_b32 m0, s50
	s_lshl_b32 s11, s49, 1
	v_mov_b32_e32 v1, v0
	v_mov_b32_e32 v2, v0
	v_mov_b32_e32 v3, v0
	v_mov_b32_e32 v4, v0
	v_mov_b32_e32 v5, v0
	v_mov_b32_e32 v6, v0
	v_mov_b32_e32 v7, v0
	v_mov_b32_e32 v8, v0
	v_mov_b32_e32 v9, v0
	v_mov_b32_e32 v10, v0
	v_mov_b32_e32 v11, v0
	v_mov_b32_e32 v12, v0
	v_mov_b32_e32 v13, v0
	v_mov_b64_e32 v[30:31], v[14:15]
	v_mov_b64_e32 v[46:47], v[14:15]
	v_mov_b64_e32 v[62:63], v[14:15]
	v_mov_b64_e32 v[78:79], v[14:15]
	v_mov_b32_e32 v155, s27
	s_mov_b32 s26, 0
	v_mov_b32_e32 v143, 0
	v_mov_b32_e32 v185, 0xff800000
	s_mov_b32 s27, 63
	s_or_b32 s29, s11, 1
	v_mov_b64_e32 v[28:29], v[12:13]
	v_mov_b64_e32 v[26:27], v[10:11]
	v_mov_b64_e32 v[24:25], v[8:9]
	v_mov_b64_e32 v[22:23], v[6:7]
	v_mov_b64_e32 v[20:21], v[4:5]
	v_mov_b64_e32 v[18:19], v[2:3]
	v_mov_b64_e32 v[16:17], v[0:1]
	s_or_b32 s49, s10, 31
	v_mov_b64_e32 v[44:45], v[12:13]
	v_mov_b64_e32 v[42:43], v[10:11]
	v_mov_b64_e32 v[40:41], v[8:9]
	v_mov_b64_e32 v[38:39], v[6:7]
	v_mov_b64_e32 v[36:37], v[4:5]
	v_mov_b64_e32 v[34:35], v[2:3]
	v_mov_b64_e32 v[32:33], v[0:1]
	v_mov_b64_e32 v[60:61], v[12:13]
	v_mov_b64_e32 v[58:59], v[10:11]
	v_mov_b64_e32 v[56:57], v[8:9]
	v_mov_b64_e32 v[54:55], v[6:7]
	v_mov_b64_e32 v[52:53], v[4:5]
	v_mov_b64_e32 v[50:51], v[2:3]
	v_mov_b64_e32 v[48:49], v[0:1]
	s_mov_b32 s30, 0
	v_mov_b64_e32 v[76:77], v[12:13]
	v_mov_b64_e32 v[74:75], v[10:11]
	v_mov_b64_e32 v[72:73], v[8:9]
	v_mov_b64_e32 v[70:71], v[6:7]
	v_mov_b64_e32 v[68:69], v[4:5]
	v_mov_b64_e32 v[66:67], v[2:3]
	v_mov_b64_e32 v[64:65], v[0:1]
	s_waitcnt vmcnt(0)
	s_waitcnt vmcnt(4) lgkmcnt(0)
	s_barrier
	s_mov_b32 s60, 0
	s_mov_b32 s61, 0
	v_mov_b32_e32 v240, 0
	v_mov_b32_e32 v241, 0
	v_mov_b32_e32 v242, 0
	v_mov_b32_e32 v243, 0
	v_mov_b32_e32 v244, 0
	v_mov_b32_e32 v245, 0
	v_mov_b32_e32 v246, 0
	v_mov_b32_e32 v247, 0
	v_mov_b32_e32 v248, 0
	v_mov_b32_e32 v249, 0
	v_mov_b32_e32 v250, 0
	v_mov_b32_e32 v251, 0
	v_mov_b32_e32 v252, 0
	v_mov_b32_e32 v253, 0
	v_mov_b32_e32 v254, 0
	v_mov_b32_e32 v255, 0
.Ldf2_loop:
	s_add_i32 s31, s30, 2
	s_cmp_lt_u32 s30, s11
	s_cselect_b32 s50, s31, s29
	s_lshl_b32 s51, s50, 6
	s_mul_i32 s50, s50, 0x60000
	s_mul_hi_u32 s51, s51, 0x1800
	s_add_u32 s50, s24, s50
	s_addc_u32 s51, s25, s51
	s_lshl_b32 s31, s31, 15
	s_and_b32 s31, s31, 0x18000
	s_add_i32 s52, s31, s22
	s_mov_b32 s53, m0
	s_mov_b32 m0, s52
	s_nop 0
	global_load_lds_dwordx4 v156, s[50:51]
	s_mov_b32 m0, s53
	s_add_i32 s52, s31, s28
	s_mov_b32 s53, m0
	s_mov_b32 m0, s52
	s_nop 0
	global_load_lds_dwordx4 v159, s[50:51]
	s_mov_b32 m0, s53
	s_add_i32 s52, s31, s36
	s_mov_b32 s53, m0
	s_mov_b32 m0, s52
	s_nop 0
	global_load_lds_dwordx4 v157, s[50:51]
	s_mov_b32 m0, s53
	s_add_i32 s31, s31, s37
	s_sub_i32 s52, s27, 63
	s_cmp_gt_u32 s52, s49
	s_mov_b32 s52, m0
	s_mov_b32 m0, s31
	s_nop 0
	global_load_lds_dwordx4 v158, s[50:51]
	s_mov_b32 m0, s52
	s_cbranch_scc1 .Ldf2_skip
	s_and_b32 s31, s26, 0x18000
	v_add_u32_e32 v2, s31, v160
	v_add_u32_e32 v3, v2, v161
	v_add_u32_e32 v4, v2, v162
	v_add_u32_e32 v5, v2, v163
	v_add_u32_e32 v2, v2, v164
	ds_read_b128 v[208:211], v3
	ds_read_b128 v[212:215], v3 offset:4096
	ds_read_b128 v[216:219], v4
	ds_read_b128 v[220:223], v4 offset:4096
	ds_read_b128 v[224:227], v5
	ds_read_b128 v[228:231], v5 offset:4096
	ds_read_b128 v[232:235], v2
	ds_read_b128 v[236:239], v2 offset:4096
	s_add_i32 s50, s26, 0x18000
	s_cmp_eq_u32 s61, 0
	s_cselect_b32 s50, s26, s50
	s_and_b32 s50, s50, 0x18000
	v_add_u32_e32 v6, s50, v165
	s_cmp_eq_u32 s60, 0
	s_cbranch_scc1 .Ldf2s_noresc
; DI f32x16 mfma32(bf16x8 a, bf16x8 b, f32x16 c) { return __builtin_amdgcn_mfma_f32_32x32x16_bf16(a, b, c, 0, 0, 0); }
; #define DF_VLD(VF, VOFF, H) do { _Pragma("unroll") for (int d2 = 0; d2 < 2; ++d2) { LAS unsigned char* vb_ = lds3 + (VOFF) + (2 * (H) + d2) * 4096; VF[2 * d2] = vfrag(vb_); VF[2 * d2 + 1] = vfrag(vb_ + 1024); } } while (0)
; #define DF_PVM(VF, P0, P1, H) do { _Pragma("unroll") for (int d2 = 0; d2 < 2; ++d2) { o[2 * (H) + d2] = mfma32(VF[2 * d2], P0, o[2 * (H) + d2]); o[2 * (H) + d2] = mfma32(VF[2 * d2 + 1], P1, o[2 * (H) + d2]); } } while (0)
; DI void diff_stage(const unsigned char* lds, LAS unsigned char* lds3, int buf, int t, int comp, int q0, int r32, int hi, int vlane, bool skew,
;                    const bf16x8 (&qf)[4], f32x16 (&o)[4], float& m, float& l, bf16x8 (&pp)[4], int& pvo, bool& have_prev) {
;     ...
;     if (skew && have_prev) {
; #pragma unroll
;         for (int sub = 0; sub < 2; ++sub) { DF_VLD(vf, pvo + sub * 2048, 0); DF_PVM(vf, pp[2 * sub], pp[2 * sub + 1], 0); DF_VLD(vf, pvo + sub * 2048, 1); DF_PVM(vf, pp[2 * sub], pp[2 * sub + 1], 1); }
;     }
;     f32x16 s0, s1;
; #pragma unroll
;     for (int i = 0; i < 16; ++i) { s0[i] = 0.f; s1[i] = 0.f; }
;     {
;         bf16x8 k0f[4], k1f[4];
; #pragma unroll
;         for (int c = 0; c < 4; ++c) { k0f[c] = *(const bf16x8*)(sb + ((32 * c) ^ ke16)); k1f[c] = *(const bf16x8*)(sb + 32 * 128 + ((32 * c) ^ ke16)); }
; #pragma unroll
;         for (int c = 0; c < 4; ++c) { s0 = mfma32(k0f[c], qf[c], s0); s1 = mfma32(k1f[c], qf[c], s1); }
;     }
;     if (k0 + 63 > q0) {
;         const int dq = q0 + r32 - k0 - 4 * hi;
; #pragma unroll
;         for (int i = 0; i < 16; ++i) { const int ci = (i & 3) + 8 * (i >> 2); s0[i] = (ci > dq) ? -INFINITY : s0[i]; s1[i] = (ci + 32 > dq) ? -INFINITY : s1[i]; }
	v_pk_mul_f32 v[78:79], v[78:79], v[206:207] op_sel_hi:[1,0]
	v_pk_mul_f32 v[76:77], v[76:77], v[206:207] op_sel_hi:[1,0]
	v_pk_mul_f32 v[74:75], v[74:75], v[206:207] op_sel_hi:[1,0]
	v_pk_mul_f32 v[72:73], v[72:73], v[206:207] op_sel_hi:[1,0]
	v_pk_mul_f32 v[70:71], v[70:71], v[206:207] op_sel_hi:[1,0]
	v_pk_mul_f32 v[68:69], v[68:69], v[206:207] op_sel_hi:[1,0]
	v_pk_mul_f32 v[66:67], v[66:67], v[206:207] op_sel_hi:[1,0]
	v_pk_mul_f32 v[64:65], v[64:65], v[206:207] op_sel_hi:[1,0]
	v_pk_mul_f32 v[62:63], v[62:63], v[206:207] op_sel_hi:[1,0]
	v_pk_mul_f32 v[60:61], v[60:61], v[206:207] op_sel_hi:[1,0]
	v_pk_mul_f32 v[58:59], v[58:59], v[206:207] op_sel_hi:[1,0]
	v_pk_mul_f32 v[56:57], v[56:57], v[206:207] op_sel_hi:[1,0]
	v_pk_mul_f32 v[54:55], v[54:55], v[206:207] op_sel_hi:[1,0]
	v_pk_mul_f32 v[52:53], v[52:53], v[206:207] op_sel_hi:[1,0]
	v_pk_mul_f32 v[50:51], v[50:51], v[206:207] op_sel_hi:[1,0]
	v_pk_mul_f32 v[48:49], v[48:49], v[206:207] op_sel_hi:[1,0]
	v_pk_mul_f32 v[46:47], v[46:47], v[206:207] op_sel_hi:[1,0]
	v_pk_mul_f32 v[44:45], v[44:45], v[206:207] op_sel_hi:[1,0]
	v_pk_mul_f32 v[42:43], v[42:43], v[206:207] op_sel_hi:[1,0]
	v_pk_mul_f32 v[40:41], v[40:41], v[206:207] op_sel_hi:[1,0]
	v_pk_mul_f32 v[38:39], v[38:39], v[206:207] op_sel_hi:[1,0]
	v_pk_mul_f32 v[36:37], v[36:37], v[206:207] op_sel_hi:[1,0]
	v_pk_mul_f32 v[34:35], v[34:35], v[206:207] op_sel_hi:[1,0]
	v_pk_mul_f32 v[32:33], v[32:33], v[206:207] op_sel_hi:[1,0]
	v_pk_mul_f32 v[30:31], v[30:31], v[206:207] op_sel_hi:[1,0]
	v_pk_mul_f32 v[28:29], v[28:29], v[206:207] op_sel_hi:[1,0]
	v_pk_mul_f32 v[26:27], v[26:27], v[206:207] op_sel_hi:[1,0]
	v_pk_mul_f32 v[24:25], v[24:25], v[206:207] op_sel_hi:[1,0]
	v_pk_mul_f32 v[22:23], v[22:23], v[206:207] op_sel_hi:[1,0]
	v_pk_mul_f32 v[20:21], v[20:21], v[206:207] op_sel_hi:[1,0]
	v_pk_mul_f32 v[18:19], v[18:19], v[206:207] op_sel_hi:[1,0]
	v_pk_mul_f32 v[16:17], v[16:17], v[206:207] op_sel_hi:[1,0]
	s_mov_b32 s60, 0
.Ldf2s_noresc:
	s_waitcnt lgkmcnt(7)
	v_mfma_f32_32x32x16_bf16 v[96:111], v[208:211], v[124:127], 0
	s_waitcnt lgkmcnt(6)
	v_mfma_f32_32x32x16_bf16 v[80:95], v[212:215], v[124:127], 0
	s_waitcnt lgkmcnt(5)
	v_mfma_f32_32x32x16_bf16 v[96:111], v[216:219], v[120:123], v[96:111]
	s_waitcnt lgkmcnt(4)
	v_mfma_f32_32x32x16_bf16 v[80:95], v[220:223], v[120:123], v[80:95]
	s_waitcnt lgkmcnt(3)
	v_mfma_f32_32x32x16_bf16 v[96:111], v[224:227], v[116:119], v[96:111]
	s_waitcnt lgkmcnt(2)
	v_mfma_f32_32x32x16_bf16 v[80:95], v[228:231], v[116:119], v[80:95]
	s_waitcnt lgkmcnt(1)
	v_mfma_f32_32x32x16_bf16 v[96:111], v[232:235], v[112:115], v[96:111]
	s_waitcnt lgkmcnt(0)
	v_mfma_f32_32x32x16_bf16 v[80:95], v[236:239], v[112:115], v[80:95]
	ds_read_b64_tr_b16 v[208:209], v6 offset:16384
	ds_read_b64_tr_b16 v[210:211], v6 offset:16896
	ds_read_b64_tr_b16 v[212:213], v6 offset:17408
	ds_read_b64_tr_b16 v[214:215], v6 offset:17920
	ds_read_b64_tr_b16 v[216:217], v6 offset:20480
	ds_read_b64_tr_b16 v[218:219], v6 offset:20992
	ds_read_b64_tr_b16 v[220:221], v6 offset:21504
	ds_read_b64_tr_b16 v[222:223], v6 offset:22016
	ds_read_b64_tr_b16 v[224:225], v6 offset:24576
	ds_read_b64_tr_b16 v[226:227], v6 offset:25088
	ds_read_b64_tr_b16 v[228:229], v6 offset:25600
	ds_read_b64_tr_b16 v[230:231], v6 offset:26112
	s_cmp_le_u32 s27, s10
	s_cbranch_scc1 .Ldf2_nodiag
	s_nop 7
	v_cmp_lt_i32_e32 vcc, -1, v183
	s_nop 1
	v_cndmask_b32_e32 v96, v176, v96, vcc
	v_cmp_lt_i32_e32 vcc, 31, v183
	s_nop 1
	v_cndmask_b32_e32 v80, v176, v80, vcc
	v_cmp_lt_i32_e32 vcc, 0, v183
	s_nop 1
	v_cndmask_b32_e32 v97, v176, v97, vcc
	v_cmp_lt_i32_e32 vcc, 32, v183
	s_nop 1
	v_cndmask_b32_e32 v81, v176, v81, vcc
	v_cmp_lt_i32_e32 vcc, 1, v183
	s_nop 1
	v_cndmask_b32_e32 v98, v176, v98, vcc
	v_cmp_lt_i32_e32 vcc, 33, v183
	s_nop 1
	v_cndmask_b32_e32 v82, v176, v82, vcc
	v_cmp_lt_i32_e32 vcc, 2, v183
	s_nop 1
	v_cndmask_b32_e32 v99, v176, v99, vcc
	v_cmp_lt_i32_e32 vcc, 34, v183
	s_nop 1
	v_cndmask_b32_e32 v83, v176, v83, vcc
	v_cmp_lt_i32_e32 vcc, 7, v183
	s_nop 1
	v_cndmask_b32_e32 v100, v176, v100, vcc
	v_cmp_lt_i32_e32 vcc, 39, v183
	s_nop 1
	v_cndmask_b32_e32 v84, v176, v84, vcc
	v_cmp_lt_i32_e32 vcc, 8, v183
	s_nop 1
	v_cndmask_b32_e32 v101, v176, v101, vcc
	v_cmp_lt_i32_e32 vcc, 40, v183
	s_nop 1
	v_cndmask_b32_e32 v85, v176, v85, vcc
	v_cmp_lt_i32_e32 vcc, 9, v183
	s_nop 1
	v_cndmask_b32_e32 v102, v176, v102, vcc
	v_cmp_lt_i32_e32 vcc, 41, v183
	s_nop 1
	v_cndmask_b32_e32 v86, v176, v86, vcc
	v_cmp_lt_i32_e32 vcc, 10, v183
	s_nop 1
	v_cndmask_b32_e32 v103, v176, v103, vcc
	v_cmp_lt_i32_e32 vcc, 42, v183
	s_nop 1
	v_cndmask_b32_e32 v87, v176, v87, vcc
	v_cmp_lt_i32_e32 vcc, 15, v183
	s_nop 1
	v_cndmask_b32_e32 v104, v176, v104, vcc
	v_cmp_lt_i32_e32 vcc, 47, v183
	s_nop 1
	v_cndmask_b32_e32 v88, v176, v88, vcc
	v_cmp_lt_i32_e32 vcc, 16, v183
	s_nop 1
	v_cndmask_b32_e32 v105, v176, v105, vcc
	v_cmp_lt_i32_e32 vcc, 48, v183
	s_nop 1
	v_cndmask_b32_e32 v89, v176, v89, vcc
	v_cmp_lt_i32_e32 vcc, 17, v183
	s_nop 1
	v_cndmask_b32_e32 v106, v176, v106, vcc
	v_cmp_lt_i32_e32 vcc, 49, v183
	s_nop 1
	v_cndmask_b32_e32 v90, v176, v90, vcc
	v_cmp_lt_i32_e32 vcc, 18, v183
	s_nop 1
	v_cndmask_b32_e32 v107, v176, v107, vcc
	v_cmp_lt_i32_e32 vcc, 50, v183
	s_nop 1
	v_cndmask_b32_e32 v91, v176, v91, vcc
	v_cmp_lt_i32_e32 vcc, 23, v183
	s_nop 1
	v_cndmask_b32_e32 v108, v176, v108, vcc
	v_cmp_lt_i32_e32 vcc, 55, v183
	s_nop 1
	v_cndmask_b32_e32 v92, v176, v92, vcc
	v_cmp_lt_i32_e32 vcc, 24, v183
	s_nop 1
	v_cndmask_b32_e32 v109, v176, v109, vcc
	v_cmp_lt_i32_e32 vcc, 56, v183
	s_nop 1
	v_cndmask_b32_e32 v93, v176, v93, vcc
	v_cmp_lt_i32_e32 vcc, 25, v183
	s_nop 1
	v_cndmask_b32_e32 v110, v176, v110, vcc
	v_cmp_lt_i32_e32 vcc, 57, v183
	s_nop 1
	v_cndmask_b32_e32 v94, v176, v94, vcc
	v_cmp_lt_i32_e32 vcc, 26, v183
	s_nop 1
	v_cndmask_b32_e32 v111, v176, v111, vcc
	v_cmp_lt_i32_e32 vcc, 58, v183
	s_nop 1
	v_cndmask_b32_e32 v95, v176, v95, vcc
; DI float xhalf(float v) { return __shfl_xor(v, 32); }
; DI float fexp2(float x) { return __builtin_amdgcn_exp2f(x); }
; #define DF_VLD(VF, VOFF, H) do { _Pragma("unroll") for (int d2 = 0; d2 < 2; ++d2) { LAS unsigned char* vb_ = lds3 + (VOFF) + (2 * (H) + d2) * 4096; VF[2 * d2] = vfrag(vb_); VF[2 * d2 + 1] = vfrag(vb_ + 1024); } } while (0)
; DI void diff_stage(const unsigned char* lds, LAS unsigned char* lds3, int buf, int t, int comp, int q0, int r32, int hi, int vlane, bool skew,
;                    const bf16x8 (&qf)[4], f32x16 (&o)[4], float& m, float& l, bf16x8 (&pp)[4], int& pvo, bool& have_prev) {
;     ...
;     if (skew && have_prev) {
; #pragma unroll
;         for (int sub = 0; sub < 2; ++sub) { DF_VLD(vf, pvo + sub * 2048, 0); DF_PVM(vf, pp[2 * sub], pp[2 * sub + 1], 0); DF_VLD(vf, pvo + sub * 2048, 1); DF_PVM(vf, pp[2 * sub], pp[2 * sub + 1], 1); }
;     }
;     ...
;     float mx = fmaxf(fmaxf(s0[0], s0[1]), s1[0]);
; #pragma unroll
;     for (int i = 1; i < 15; i += 2) { mx = fmaxf(fmaxf(mx, s0[i + 1]), s0[i + 2 > 15 ? 15 : i + 2]); mx = fmaxf(fmaxf(mx, s1[i]), s1[i + 1]); }
;     mx = fmaxf(mx, s1[15]);
;     mx = fmaxf(mx, xhalf(mx)) * SCL2;
;     if (__any(mx > m + 8.f)) {
;         const float mn = fmaxf(m, mx), al = fexp2(m - mn); l *= al; m = mn;
; #pragma unroll
;         for (int dt = 0; dt < 4; ++dt)
; #pragma unroll
;             for (int i = 0; i < 16; ++i) o[dt][i] *= al;
;     }
;     float sum0 = 0.f, sum1 = 0.f;
; #pragma unroll
;     for (int i = 0; i < 16; ++i) { s0[i] = fexp2(__builtin_fmaf(s0[i], SCL2, -m)); sum0 += s0[i]; s1[i] = fexp2(__builtin_fmaf(s1[i], SCL2, -m)); sum1 += s1[i]; }
;     l += sum0 + sum1;
;     const int vo = buf * DF_STAGE + DF_V + vlane;
;     if (!skew) {
;         const bf16x8 p00 = packP<0>(s0), p01 = packP<1>(s0);
;         DF_VLD(vf, vo, 0); DF_PVM(vf, p00, p01, 0); DF_VLD(vf, vo, 1); DF_PVM(vf, p00, p01, 1);
;         const bf16x8 p10 = packP<0>(s1), p11 = packP<1>(s1);
;         DF_VLD(vf, vo + 2048, 0); DF_PVM(vf, p10, p11, 0); DF_VLD(vf, vo + 2048, 1); DF_PVM(vf, p10, p11, 1);
;     } else { pp[0] = packP<0>(s0); pp[1] = packP<1>(s0); pp[2] = packP<0>(s1); pp[3] = packP<1>(s1); pvo = vo; have_prev = true; }
.Ldf2_nodiag:
	s_waitcnt lgkmcnt(10)
	v_mfma_f32_32x32x16_bf16 v[64:79], v[208:211], v[240:243], v[64:79]
	ds_read_b64_tr_b16 v[232:233], v6 offset:28672
	ds_read_b64_tr_b16 v[234:235], v6 offset:29184
	v_max3_f32 v1, v96, v97, v98
	v_max3_f32 v1, v1, v99, v100
	v_max3_f32 v1, v1, v101, v102
	v_max3_f32 v1, v1, v103, v104
	v_max3_f32 v1, v1, v105, v106
	v_max3_f32 v1, v1, v107, v108
	v_max3_f32 v1, v1, v109, v110
	v_max3_f32 v1, v1, v111, v80
	s_waitcnt lgkmcnt(10)
	v_mfma_f32_32x32x16_bf16 v[64:79], v[212:215], v[244:247], v[64:79]
	ds_read_b64_tr_b16 v[236:237], v6 offset:29696
	ds_read_b64_tr_b16 v[238:239], v6 offset:30208
	v_max3_f32 v1, v1, v81, v82
	v_max3_f32 v1, v1, v83, v84
	v_max3_f32 v1, v1, v85, v86
	v_max3_f32 v1, v1, v87, v88
	v_max3_f32 v1, v1, v89, v90
	v_max3_f32 v1, v1, v91, v92
	v_max3_f32 v1, v1, v93, v94
	v_max_f32_e32 v1, v1, v95
	s_waitcnt lgkmcnt(10)
	v_mfma_f32_32x32x16_bf16 v[48:63], v[216:219], v[240:243], v[48:63]
	ds_read_b64_tr_b16 v[208:209], v6 offset:18432
	ds_read_b64_tr_b16 v[210:211], v6 offset:18944
	v_mov_b32_e32 v14, v1
	s_nop 1
	v_permlane32_swap_b32_e32 v1, v14
	v_add_f32_e32 v15, 0x41000000, v185
	v_max_f32_e32 v1, v1, v14
	v_mul_f32_e32 v1, 0x3e38aa3b, v1
	v_cmp_gt_f32_e32 vcc, v1, v15
	s_cbranch_vccz .Ldf2_notrig
	v_max_f32_e32 v1, v1, v1
	v_max_f32_e32 v14, v185, v185
	v_max_f32_e32 v1, v14, v1
	v_sub_f32_e32 v14, v185, v1
	v_exp_f32_e32 v206, v14
	v_mov_b32_e32 v185, v1
	s_mov_b32 s60, 1
	v_mul_f32_e32 v143, v143, v206
.Ldf2_notrig:
	s_waitcnt lgkmcnt(10)
	v_mfma_f32_32x32x16_bf16 v[48:63], v[220:223], v[244:247], v[48:63]
	ds_read_b64_tr_b16 v[212:213], v6 offset:19456
	ds_read_b64_tr_b16 v[214:215], v6 offset:19968
	v_fma_f32 v96, v96, s44, -v185
	v_fma_f32 v97, v97, s44, -v185
	v_exp_f32_e32 v96, v96
	v_exp_f32_e32 v97, v97
	v_fma_f32 v98, v98, s44, -v185
	v_fma_f32 v99, v99, s44, -v185
	v_exp_f32_e32 v98, v98
	v_exp_f32_e32 v99, v99
	s_waitcnt lgkmcnt(10)
	v_mfma_f32_32x32x16_bf16 v[32:47], v[224:227], v[240:243], v[32:47]
	ds_read_b64_tr_b16 v[216:217], v6 offset:22528
	ds_read_b64_tr_b16 v[218:219], v6 offset:23040
	v_fma_f32 v100, v100, s44, -v185
	v_fma_f32 v101, v101, s44, -v185
	v_exp_f32_e32 v100, v100
	v_exp_f32_e32 v101, v101
	v_fma_f32 v102, v102, s44, -v185
	v_fma_f32 v103, v103, s44, -v185
	v_exp_f32_e32 v102, v102
	v_exp_f32_e32 v103, v103
	s_waitcnt lgkmcnt(10)
	v_mfma_f32_32x32x16_bf16 v[32:47], v[228:231], v[244:247], v[32:47]
	ds_read_b64_tr_b16 v[220:221], v6 offset:23552
	ds_read_b64_tr_b16 v[222:223], v6 offset:24064
	v_fma_f32 v104, v104, s44, -v185
	v_fma_f32 v105, v105, s44, -v185
	v_exp_f32_e32 v104, v104
	v_exp_f32_e32 v105, v105
	v_fma_f32 v106, v106, s44, -v185
	v_fma_f32 v107, v107, s44, -v185
	v_exp_f32_e32 v106, v106
	v_exp_f32_e32 v107, v107
	s_waitcnt lgkmcnt(10)
	v_mfma_f32_32x32x16_bf16 v[16:31], v[232:235], v[240:243], v[16:31]
	ds_read_b64_tr_b16 v[224:225], v6 offset:26624
	ds_read_b64_tr_b16 v[226:227], v6 offset:27136
	v_fma_f32 v108, v108, s44, -v185
	v_fma_f32 v109, v109, s44, -v185
	v_exp_f32_e32 v108, v108
	v_exp_f32_e32 v109, v109
	v_fma_f32 v110, v110, s44, -v185
	v_fma_f32 v111, v111, s44, -v185
	v_exp_f32_e32 v110, v110
	v_exp_f32_e32 v111, v111
	s_waitcnt lgkmcnt(10)
	v_mfma_f32_32x32x16_bf16 v[16:31], v[236:239], v[244:247], v[16:31]
	ds_read_b64_tr_b16 v[228:229], v6 offset:27648
	ds_read_b64_tr_b16 v[230:231], v6 offset:28160
	v_add_f32_e32 v14, v96, v97
	v_add_f32_e32 v14, v14, v98
	v_add_f32_e32 v14, v14, v99
	v_add_f32_e32 v14, v14, v100
	v_add_f32_e32 v14, v14, v101
	v_add_f32_e32 v14, v14, v102
	v_add_f32_e32 v14, v14, v103
	v_add_f32_e32 v14, v14, v104
	s_waitcnt lgkmcnt(10)
	v_mfma_f32_32x32x16_bf16 v[64:79], v[208:211], v[248:251], v[64:79]
	ds_read_b64_tr_b16 v[232:233], v6 offset:30720
	ds_read_b64_tr_b16 v[234:235], v6 offset:31232
	v_cvt_pk_bf16_f32 v240, v96, v97
	v_cvt_pk_bf16_f32 v241, v98, v99
	v_cvt_pk_bf16_f32 v242, v100, v101
	v_cvt_pk_bf16_f32 v243, v102, v103
	v_cvt_pk_bf16_f32 v244, v104, v105
	v_cvt_pk_bf16_f32 v245, v106, v107
	v_cvt_pk_bf16_f32 v246, v108, v109
	v_cvt_pk_bf16_f32 v247, v110, v111
	s_waitcnt lgkmcnt(10)
	v_mfma_f32_32x32x16_bf16 v[64:79], v[212:215], v[252:255], v[64:79]
	ds_read_b64_tr_b16 v[236:237], v6 offset:31744
	ds_read_b64_tr_b16 v[238:239], v6 offset:32256
	v_add_f32_e32 v14, v14, v105
	v_add_f32_e32 v14, v14, v106
	v_add_f32_e32 v14, v14, v107
	v_add_f32_e32 v14, v14, v108
	v_add_f32_e32 v14, v14, v109
	v_add_f32_e32 v14, v14, v110
	v_add_f32_e32 v14, v14, v111
	v_fma_f32 v80, v80, s44, -v185
	s_waitcnt lgkmcnt(10)
	v_mfma_f32_32x32x16_bf16 v[48:63], v[216:219], v[248:251], v[48:63]
	v_fma_f32 v81, v81, s44, -v185
	v_exp_f32_e32 v80, v80
	v_exp_f32_e32 v81, v81
	v_fma_f32 v82, v82, s44, -v185
	v_fma_f32 v83, v83, s44, -v185
	v_exp_f32_e32 v82, v82
	v_exp_f32_e32 v83, v83
	v_fma_f32 v84, v84, s44, -v185
	s_waitcnt lgkmcnt(8)
	v_mfma_f32_32x32x16_bf16 v[48:63], v[220:223], v[252:255], v[48:63]
	v_fma_f32 v85, v85, s44, -v185
	v_exp_f32_e32 v84, v84
	v_exp_f32_e32 v85, v85
	v_fma_f32 v86, v86, s44, -v185
	v_fma_f32 v87, v87, s44, -v185
	v_exp_f32_e32 v86, v86
	v_exp_f32_e32 v87, v87
	v_fma_f32 v88, v88, s44, -v185
	s_waitcnt lgkmcnt(6)
	v_mfma_f32_32x32x16_bf16 v[32:47], v[224:227], v[248:251], v[32:47]
	v_fma_f32 v89, v89, s44, -v185
	v_exp_f32_e32 v88, v88
	v_exp_f32_e32 v89, v89
	v_fma_f32 v90, v90, s44, -v185
	v_fma_f32 v91, v91, s44, -v185
	v_exp_f32_e32 v90, v90
	v_exp_f32_e32 v91, v91
	v_fma_f32 v92, v92, s44, -v185
	s_waitcnt lgkmcnt(4)
	v_mfma_f32_32x32x16_bf16 v[32:47], v[228:231], v[252:255], v[32:47]
	v_fma_f32 v93, v93, s44, -v185
	v_exp_f32_e32 v92, v92
	v_exp_f32_e32 v93, v93
	v_fma_f32 v94, v94, s44, -v185
	v_fma_f32 v95, v95, s44, -v185
	v_exp_f32_e32 v94, v94
	v_exp_f32_e32 v95, v95
	v_add_f32_e32 v15, v80, v81
	s_waitcnt lgkmcnt(2)
	v_mfma_f32_32x32x16_bf16 v[16:31], v[232:235], v[248:251], v[16:31]
	v_add_f32_e32 v15, v15, v82
	v_add_f32_e32 v15, v15, v83
	v_add_f32_e32 v15, v15, v84
	v_add_f32_e32 v15, v15, v85
	v_add_f32_e32 v15, v15, v86
	v_add_f32_e32 v15, v15, v87
	v_add_f32_e32 v15, v15, v88
	v_add_f32_e32 v15, v15, v89
	s_waitcnt lgkmcnt(0)
	v_mfma_f32_32x32x16_bf16 v[16:31], v[236:239], v[252:255], v[16:31]
	v_add_f32_e32 v15, v15, v90
	v_add_f32_e32 v15, v15, v91
	v_add_f32_e32 v15, v15, v92
	v_add_f32_e32 v15, v15, v93
	v_add_f32_e32 v15, v15, v94
	v_add_f32_e32 v15, v15, v95
	v_add_f32_e32 v14, v14, v15
	v_add_f32_e32 v143, v143, v14
	v_cvt_pk_bf16_f32 v248, v80, v81
	v_cvt_pk_bf16_f32 v249, v82, v83
	v_cvt_pk_bf16_f32 v250, v84, v85
	v_cvt_pk_bf16_f32 v251, v86, v87
	v_cvt_pk_bf16_f32 v252, v88, v89
	v_cvt_pk_bf16_f32 v253, v90, v91
	v_cvt_pk_bf16_f32 v254, v92, v93
	v_cvt_pk_bf16_f32 v255, v94, v95
	s_mov_b32 s61, 1
	s_branch .Ldf2_bar
; #define DF_VLD(VF, VOFF, H) do { _Pragma("unroll") for (int d2 = 0; d2 < 2; ++d2) { LAS unsigned char* vb_ = lds3 + (VOFF) + (2 * (H) + d2) * 4096; VF[2 * d2] = vfrag(vb_); VF[2 * d2 + 1] = vfrag(vb_ + 1024); } } while (0)
; #define DF_PVM(VF, P0, P1, H) do { _Pragma("unroll") for (int d2 = 0; d2 < 2; ++d2) { o[2 * (H) + d2] = mfma32(VF[2 * d2], P0, o[2 * (H) + d2]); o[2 * (H) + d2] = mfma32(VF[2 * d2 + 1], P1, o[2 * (H) + d2]); } } while (0)
; DI void diff_stage(const unsigned char* lds, LAS unsigned char* lds3, int buf, int t, int comp, int q0, int r32, int hi, int vlane, bool skew,
;                    const bf16x8 (&qf)[4], f32x16 (&o)[4], float& m, float& l, bf16x8 (&pp)[4], int& pvo, bool& have_prev) {
;     ...
;     if (k0 > q0 + 31) return;
;     const unsigned char* sb = lds + buf * DF_STAGE + comp * DF_K2 + r32 * 128; const int ke16 = (hi ^ ((r32 >> 1) & 7)) * 16;
;     bf16x8 vf[4];
;     if (skew && have_prev) {
; #pragma unroll
;         for (int sub = 0; sub < 2; ++sub) { DF_VLD(vf, pvo + sub * 2048, 0); DF_PVM(vf, pp[2 * sub], pp[2 * sub + 1], 0); DF_VLD(vf, pvo + sub * 2048, 1); DF_PVM(vf, pp[2 * sub], pp[2 * sub + 1], 1); }
;     }
.Ldf2_skip:
	s_cmp_eq_u32 s61, 0
	s_cbranch_scc1 .Ldf2_bar
	s_add_i32 s50, s26, 0x18000
	s_and_b32 s50, s50, 0x18000
	v_add_u32_e32 v6, s50, v165
	s_cmp_eq_u32 s60, 0
	s_cbranch_scc1 .Ldf2k_noresc
	v_pk_mul_f32 v[78:79], v[78:79], v[206:207] op_sel_hi:[1,0]
	v_pk_mul_f32 v[76:77], v[76:77], v[206:207] op_sel_hi:[1,0]
	v_pk_mul_f32 v[74:75], v[74:75], v[206:207] op_sel_hi:[1,0]
	v_pk_mul_f32 v[72:73], v[72:73], v[206:207] op_sel_hi:[1,0]
	v_pk_mul_f32 v[70:71], v[70:71], v[206:207] op_sel_hi:[1,0]
	v_pk_mul_f32 v[68:69], v[68:69], v[206:207] op_sel_hi:[1,0]
	v_pk_mul_f32 v[66:67], v[66:67], v[206:207] op_sel_hi:[1,0]
	v_pk_mul_f32 v[64:65], v[64:65], v[206:207] op_sel_hi:[1,0]
	v_pk_mul_f32 v[62:63], v[62:63], v[206:207] op_sel_hi:[1,0]
	v_pk_mul_f32 v[60:61], v[60:61], v[206:207] op_sel_hi:[1,0]
	v_pk_mul_f32 v[58:59], v[58:59], v[206:207] op_sel_hi:[1,0]
	v_pk_mul_f32 v[56:57], v[56:57], v[206:207] op_sel_hi:[1,0]
	v_pk_mul_f32 v[54:55], v[54:55], v[206:207] op_sel_hi:[1,0]
	v_pk_mul_f32 v[52:53], v[52:53], v[206:207] op_sel_hi:[1,0]
	v_pk_mul_f32 v[50:51], v[50:51], v[206:207] op_sel_hi:[1,0]
	v_pk_mul_f32 v[48:49], v[48:49], v[206:207] op_sel_hi:[1,0]
	v_pk_mul_f32 v[46:47], v[46:47], v[206:207] op_sel_hi:[1,0]
	v_pk_mul_f32 v[44:45], v[44:45], v[206:207] op_sel_hi:[1,0]
	v_pk_mul_f32 v[42:43], v[42:43], v[206:207] op_sel_hi:[1,0]
	v_pk_mul_f32 v[40:41], v[40:41], v[206:207] op_sel_hi:[1,0]
	v_pk_mul_f32 v[38:39], v[38:39], v[206:207] op_sel_hi:[1,0]
	v_pk_mul_f32 v[36:37], v[36:37], v[206:207] op_sel_hi:[1,0]
	v_pk_mul_f32 v[34:35], v[34:35], v[206:207] op_sel_hi:[1,0]
	v_pk_mul_f32 v[32:33], v[32:33], v[206:207] op_sel_hi:[1,0]
	v_pk_mul_f32 v[30:31], v[30:31], v[206:207] op_sel_hi:[1,0]
	v_pk_mul_f32 v[28:29], v[28:29], v[206:207] op_sel_hi:[1,0]
	v_pk_mul_f32 v[26:27], v[26:27], v[206:207] op_sel_hi:[1,0]
	v_pk_mul_f32 v[24:25], v[24:25], v[206:207] op_sel_hi:[1,0]
	v_pk_mul_f32 v[22:23], v[22:23], v[206:207] op_sel_hi:[1,0]
	v_pk_mul_f32 v[20:21], v[20:21], v[206:207] op_sel_hi:[1,0]
	v_pk_mul_f32 v[18:19], v[18:19], v[206:207] op_sel_hi:[1,0]
	v_pk_mul_f32 v[16:17], v[16:17], v[206:207] op_sel_hi:[1,0]
	s_mov_b32 s60, 0

; __global__ void __launch_bounds__(NTHR, 2) mega_fwd(Args KA) {
;     __shared__ __attribute__((aligned(16))) unsigned char lds[139264];
	.amdhsa_kernel _Z8mega_fwd4Args
		.amdhsa_group_segment_fixed_size 139280
		.amdhsa_private_segment_fixed_size 0
		.amdhsa_kernarg_size 440
		.amdhsa_user_sgpr_count 2
		.amdhsa_user_sgpr_dispatch_ptr 0
		.amdhsa_user_sgpr_queue_ptr 0
		.amdhsa_user_sgpr_kernarg_segment_ptr 1
		.amdhsa_user_sgpr_dispatch_id 0
		.amdhsa_user_sgpr_kernarg_preload_length 0
		.amdhsa_user_sgpr_kernarg_preload_offset 0
		.amdhsa_user_sgpr_private_segment_size 0
		.amdhsa_uses_dynamic_stack 0
		.amdhsa_enable_private_segment 0
		.amdhsa_system_sgpr_workgroup_id_x 1
		.amdhsa_system_sgpr_workgroup_id_y 0
		.amdhsa_system_sgpr_workgroup_id_z 0
		.amdhsa_system_sgpr_workgroup_info 0
		.amdhsa_system_vgpr_workitem_id 2
		.amdhsa_next_free_vgpr 256
		.amdhsa_next_free_sgpr 96
		.amdhsa_accum_offset 256
		.amdhsa_reserve_vcc 1
		.amdhsa_float_round_mode_32 0
		.amdhsa_float_round_mode_16_64 0
		.amdhsa_float_denorm_mode_32 3
		.amdhsa_float_denorm_mode_16_64 3
		.amdhsa_dx10_clamp 1
		.amdhsa_ieee_mode 1
		.amdhsa_fp16_overflow 0
		.amdhsa_tg_split 0
		.amdhsa_exception_fp_ieee_invalid_op 0
		.amdhsa_exception_fp_denorm_src 0
		.amdhsa_exception_fp_ieee_div_zero 0
		.amdhsa_exception_fp_ieee_overflow 0
		.amdhsa_exception_fp_ieee_underflow 0
		.amdhsa_exception_fp_ieee_inexact 0
		.amdhsa_exception_int_div_zero 0
	.end_amdhsa_kernel

; __global__ void __launch_bounds__(NTHR, 2) mega_fwd(Args KA) {
;     __shared__ __attribute__((aligned(16))) unsigned char lds[139264];
amdhsa.kernels:
  - .agpr_count:     0
    .args:
      - .offset:         0
        .size:           184
        .value_kind:     by_value
      - .offset:         184
        .size:           4
        .value_kind:     hidden_block_count_x
      - .offset:         188
        .size:           4
        .value_kind:     hidden_block_count_y
      - .offset:         192
        .size:           4
        .value_kind:     hidden_block_count_z
      - .offset:         196
        .size:           2
        .value_kind:     hidden_group_size_x
      - .offset:         198
        .size:           2
        .value_kind:     hidden_group_size_y
      - .offset:         200
        .size:           2
        .value_kind:     hidden_group_size_z
      - .offset:         202
        .size:           2
        .value_kind:     hidden_remainder_x
      - .offset:         204
        .size:           2
        .value_kind:     hidden_remainder_y
      - .offset:         206
        .size:           2
        .value_kind:     hidden_remainder_z
      - .offset:         224
        .size:           8
        .value_kind:     hidden_global_offset_x
      - .offset:         232
        .size:           8
        .value_kind:     hidden_global_offset_y
      - .offset:         240
        .size:           8
        .value_kind:     hidden_global_offset_z
      - .offset:         248
        .size:           2
        .value_kind:     hidden_grid_dims
      - .offset:         272
        .size:           8
        .value_kind:     hidden_multigrid_sync_arg
    .group_segment_fixed_size: 139280
    .kernarg_segment_align: 8
    .kernarg_segment_size: 440
    .language:       OpenCL C
    .language_version:
      - 2
      - 0
    .max_flat_workgroup_size: 512
    .name:           _Z8mega_fwd4Args
    .private_segment_fixed_size: 0
    .sgpr_count:     94
    .sgpr_spill_count: 0
    .symbol:         _Z8mega_fwd4Args.kd
    .uniform_work_group_size: 1
    .uses_dynamic_stack: false
    .vgpr_count:     256
    .vgpr_spill_count: 0
    .wavefront_size: 64
